# GEMM epilogues (merge end, out-proj fp16-residual): gate/residual loads prefetched so no vmcnt(0) drains the previous store; ret_kv staging loads issued together
# speedup vs baseline: 1.0519x; 1.0233x over previous
; #define LAS __attribute__((address_space(3)))
; __device__ __forceinline__ float ret_logg(int h) { return log1pf(-exp2f(-5.f - (float)h)); }
; template <bool ZETA>
; __device__ __forceinline__ void ret_stage(const Params& p, LAS unsigned char* lds, int tb, int h, int c, float logg, int tid) {
;     const half_t* PR = (const half_t*)(p.ws + WS_PROJ); const float* rot = (const float*)(p.ws + WS_ROT);
;     LAS half_t* Ks = (LAS half_t*)lds; LAS half_t* Vs = (LAS half_t*)(lds + RV_OFF);
; #pragma unroll
;     for (int i = 0; i < 2; ++i) { const int id = tid + 512 * i, pos = id >> 3, ch = id & 7;
;         const half_t* src = PR + (size_t)(tb + pos) * NIN + C_RK + h * 128 + ch * 8;
;         const h8 x1 = *(const h8*)src, x2 = *(const h8*)(src + 64);
;         const float* cp = rot + (size_t)(c * 128 + pos) * 64 + ch * 8; const float* sp = cp + SEQ * 64;
;         const f32x4 c0 = *(const f32x4*)cp, c1 = *(const f32x4*)(cp + 4), s0 = *(const f32x4*)sp, s1 = *(const f32x4*)(sp + 4);
;         float sc = 0.08838834764831845f; if (ZETA) sc *= __expf(logg * (float)(127 - pos));
; __device__ __forceinline__ void ret_kv_item(const Params& p, LAS unsigned char* lds, int item, int tid, int wave, int lane) {
;     const int b = item >> 8, h = (item >> 5) & 7, c = item & 31, tb = b * SEQ + c * 128;
;     const float logg = ret_logg(h);
.LBB0_389:
	s_cmpk_gt_i32 s9, 0x1ff
	s_mov_b64 s[0:1], -1
	s_cbranch_scc0 .LBB0_393
	s_add_i32 s0, s9, 0xfffffe00
	s_bfe_u32 s5, s9, 0x30005
	s_lshl_b32 s4, s0, 7
	v_cvt_f32_ubyte0_e32 v0, s5
	s_and_b32 s10, s4, 0xf80
	v_sub_f32_e32 v0, 0xc0a00000, v0
	s_mov_b32 s4, 0xc2fc0000
	v_cmp_gt_f32_e32 vcc, s4, v0
	s_lshl_b32 s1, s0, 4
	s_and_b32 s1, s1, 0x1000
	v_cndmask_b32_e32 v1, 0, v185, vcc
	v_add_f32_e32 v0, v0, v1
	v_exp_f32_e32 v0, v0
	s_or_b32 s1, s1, s10
	s_and_b64 s[12:13], vcc, exec
	s_cselect_b32 s11, 0xffffffc0, 0
	v_ldexp_f32 v2, v0, s11
	v_sub_f32_e32 v4, 1.0, v2
	v_add_f32_e32 v0, -1.0, v4
	v_sub_f32_e32 v1, v0, v4
	v_add_f32_e32 v1, 1.0, v1
	v_sub_f32_e64 v0, -v2, v0
	v_add_f32_e32 v5, v0, v1
	v_frexp_mant_f32_e32 v0, v4
	s_mov_b32 s11, 0x3f2aaaab
	v_cmp_gt_f32_e32 vcc, s11, v0
	v_cvt_f64_f32_e32 v[0:1], v4
	v_frexp_exp_i32_f64_e32 v0, v[0:1]
	v_subbrev_co_u32_e32 v10, vcc, 0, v0, vcc
	v_sub_u32_e32 v0, 0, v10
	v_ldexp_f32 v1, v4, v0
	v_add_f32_e32 v4, -1.0, v1
	v_add_f32_e32 v6, 1.0, v1
	v_ldexp_f32 v0, v5, v0
	v_add_f32_e32 v5, 1.0, v4
	v_add_f32_e32 v7, -1.0, v6
	v_sub_f32_e32 v5, v1, v5
	v_sub_f32_e32 v1, v1, v7
	v_add_f32_e32 v5, v0, v5
	v_add_f32_e32 v0, v0, v1
	v_add_f32_e32 v11, v6, v0
	v_rcp_f32_e32 v13, v11
	v_sub_f32_e32 v1, v11, v6
	v_sub_f32_e32 v12, v0, v1
	v_add_f32_e32 v1, v4, v5
	v_mul_f32_e32 v15, v1, v13
	v_sub_f32_e32 v0, v1, v4
	v_mul_f32_e32 v4, v11, v15
	v_fma_f32 v6, v15, v11, -v4
	v_fmac_f32_e32 v6, v15, v12
	v_sub_f32_e32 v14, v5, v0
	v_add_f32_e32 v0, v4, v6
	v_sub_f32_e32 v5, v1, v0
	v_pk_add_f32 v[8:9], v[0:1], v[4:5] neg_lo:[0,1] neg_hi:[0,1]
	v_mov_b32_e32 v7, v0
	v_pk_add_f32 v[0:1], v[8:9], v[6:7] neg_lo:[0,1] neg_hi:[0,1]
	s_mov_b32 s11, 0x3f317218
	v_add_f32_e32 v1, v14, v1
	v_add_f32_e32 v0, v0, v1
	v_add_f32_e32 v1, v5, v0
	v_mul_f32_e32 v14, v13, v1
	v_mul_f32_e32 v4, v11, v14
	v_fma_f32 v6, v14, v11, -v4
	v_fmac_f32_e32 v6, v14, v12
	v_sub_f32_e32 v5, v5, v1
	v_add_f32_e32 v11, v0, v5
	v_add_f32_e32 v0, v4, v6
	v_sub_f32_e32 v5, v1, v0
	v_pk_add_f32 v[8:9], v[0:1], v[4:5] neg_lo:[0,1] neg_hi:[0,1]
	v_mov_b32_e32 v7, v0
	v_pk_add_f32 v[0:1], v[8:9], v[6:7] neg_lo:[0,1] neg_hi:[0,1]
	v_cmp_nlt_f32_e32 vcc, 1.0, v2
	v_add_f32_e32 v1, v11, v1
	v_add_f32_e32 v0, v0, v1
	v_add_f32_e32 v1, v15, v14
	v_add_f32_e32 v0, v5, v0
	v_sub_f32_e32 v4, v1, v15
	v_mul_f32_e32 v0, v13, v0
	v_sub_f32_e32 v4, v14, v4
	v_add_f32_e32 v4, v4, v0
	v_add_f32_e32 v6, v1, v4
	v_mul_f32_e32 v7, v6, v6
	v_fmamk_f32 v0, v7, 0x3e9b6dac, v184
	v_fmaak_f32 v157, v7, v0, 0x3f2aaada
	v_cvt_f32_i32_e32 v0, v10
	v_sub_f32_e32 v1, v6, v1
	v_sub_f32_e32 v1, v4, v1
	v_ldexp_f32 v8, v1, 1
	v_mul_f32_e32 v1, v6, v7
	v_ldexp_f32 v5, v6, 1
	v_pk_mul_f32 v[6:7], v[0:1], v[156:157]
	s_lshl_b32 s20, s5, 8
	v_fma_f32 v4, v0, s11, -v6
	v_fmac_f32_e32 v4, 0xb102e308, v0
	v_pk_add_f32 v[0:1], v[6:7], v[4:5]
	s_mov_b32 s11, 0x33800000
	v_sub_f32_e32 v5, v1, v5
	v_sub_f32_e32 v5, v7, v5
	v_add_f32_e32 v9, v8, v5
	v_mov_b32_e32 v8, v6
	v_pk_add_f32 v[6:7], v[0:1], v[6:7] neg_lo:[0,1] neg_hi:[0,1]
	v_pk_add_f32 v[10:11], v[0:1], v[8:9]
	v_mov_b32_e32 v5, v0
	v_mov_b32_e32 v7, v11
	v_pk_add_f32 v[12:13], v[4:5], v[6:7] neg_lo:[0,1] neg_hi:[0,1]
	v_pk_add_f32 v[4:5], v[4:5], v[6:7]
	v_mov_b32_e32 v16, v1
	v_pk_add_f32 v[6:7], v[4:5], v[0:1] op_sel:[1,0] op_sel_hi:[0,1] neg_lo:[0,1] neg_hi:[0,1]
	v_pk_add_f32 v[14:15], v[10:11], v[6:7] op_sel_hi:[1,0] neg_lo:[0,1] neg_hi:[0,1]
	v_mov_b32_e32 v10, v11
	v_mov_b32_e32 v11, v5
	v_mov_b32_e32 v17, v6
	v_pk_add_f32 v[6:7], v[10:11], v[16:17] neg_lo:[0,1] neg_hi:[0,1]
	v_mov_b32_e32 v8, v9
	v_mov_b32_e32 v9, v0
	v_pk_add_f32 v[0:1], v[8:9], v[6:7] neg_lo:[0,1] neg_hi:[0,1]
	v_mov_b32_e32 v14, v12
	v_pk_add_f32 v[6:7], v[14:15], v[0:1]
	v_mov_b32_e32 v13, v5
	v_pk_add_f32 v[8:9], v[6:7], v[6:7] op_sel:[0,1] op_sel_hi:[1,0]
	v_mov_b32_e32 v85, v3
	v_pk_add_f32 v[4:5], v[4:5], v[8:9] op_sel:[1,0] op_sel_hi:[0,1]
	v_mov_b32_e32 v7, v4
	v_pk_add_f32 v[10:11], v[6:7], v[12:13] neg_lo:[0,1] neg_hi:[0,1]
	v_mov_b32_e32 v1, v8
	v_sub_f32_e32 v5, v6, v10
	v_pk_add_f32 v[0:1], v[0:1], v[10:11] neg_lo:[0,1] neg_hi:[0,1]
	v_sub_f32_e32 v5, v12, v5
	v_add_f32_e32 v0, v0, v5
	v_add_f32_e32 v0, v0, v1
	v_add_f32_e32 v0, v4, v0
	v_cndmask_b32_e32 v0, v186, v0, vcc
	v_cmp_neq_f32_e32 vcc, 1.0, v2
	v_add_u32_e32 v4, s1, v75
	v_add_u32_e32 v12, s10, v75
	v_cndmask_b32_e32 v0, v187, v0, vcc
	v_cmp_gt_f32_e32 vcc, s11, v2
	v_ashrrev_i32_e32 v13, 31, v12
	v_lshlrev_b64 v[12:13], 8, v[12:13]
	v_cndmask_b32_e64 v2, v0, -v2, vcc
	v_mov_b64_e32 v[0:1], s[36:37]
	v_mad_i64_i32 v[4:5], s[12:13], v4, s35, v[0:1]
	v_lshl_add_u64 v[4:5], v[4:5], 0, s[20:21]
	v_lshl_add_u64 v[4:5], v[4:5], 0, v[84:85]
	global_load_dwordx4 v[8:11], v[4:5], off offset:2048
	s_nop 0
	global_load_dwordx4 v[4:7], v[4:5], off offset:2176
	v_lshl_add_u64 v[20:21], v[68:69], 0, v[12:13]
	s_mov_b64 s[14:15], 0x100000
	s_mov_b32 s11, 0x100000
	v_lshl_add_u64 v[24:25], v[20:21], 0, s[14:15]
	global_load_dwordx4 v[12:15], v[20:21], off offset:16
	global_load_dwordx4 v[16:19], v[20:21], off
	v_add_co_u32_e32 v20, vcc, s11, v20
	v_mul_f32_e32 v28, v2, v90
	s_nop 0
	v_addc_co_u32_e32 v21, vcc, 0, v21, vcc
	global_load_dwordx4 v[20:23], v[20:21], off
	s_nop 0
	global_load_dwordx4 v[24:27], v[24:25], off offset:16
	v_mul_f32_e32 v28, 0x3fb8aa3b, v28
	v_exp_f32_e32 v28, v28
	v_mul_f32_e32 v2, v2, v91
	v_mul_f32_e32 v2, 0x3fb8aa3b, v2
	v_exp_f32_e32 v2, v2
	v_mul_f32_e32 v28, 0x3db504f3, v28
	v_mov_b32_e32 v87, v3
	s_lshl_b32 s0, s0, 16
	v_mul_f32_e32 v2, 0x3db504f3, v2
	s_mov_b32 s4, 0
	v_add_u32_e32 v192, s1, v71
	v_mad_i64_i32 v[192:193], s[12:13], v192, s35, v[0:1]
; #define LAS __attribute__((address_space(3)))
; template <bool ZETA>
; __device__ __forceinline__ void ret_stage(const Params& p, LAS unsigned char* lds, int tb, int h, int c, float logg, int tid) {
;     ...
;     for (int i = 0; i < 2; ++i) { const int id = tid + 512 * i, pos = id >> 3, ch = id & 7;
;         const half_t* src = PR + (size_t)(tb + pos) * NIN + C_RK + h * 128 + ch * 8;
;         const h8 x1 = *(const h8*)src, x2 = *(const h8*)(src + 64);
;         const float* cp = rot + (size_t)(c * 128 + pos) * 64 + ch * 8; const float* sp = cp + SEQ * 64;
;         const f32x4 c0 = *(const f32x4*)cp, c1 = *(const f32x4*)(cp + 4), s0 = *(const f32x4*)sp, s1 = *(const f32x4*)(sp + 4);
;         float sc = 0.08838834764831845f; if (ZETA) sc *= __expf(logg * (float)(127 - pos));
;         h8 y1, y2;
; #pragma unroll
;         for (int e = 0; e < 8; ++e) { const float co = e < 4 ? c0[e & 3] : c1[e & 3], si = e < 4 ? s0[e & 3] : s1[e & 3]; const float a = (float)x1[e], b = (float)x2[e];
;             y1[e] = (half_t)((a * co - b * si) * sc); y2[e] = (half_t)((b * co + a * si) * sc); }
;         *(LAS h8*)(Ks + pos * KSTR + ch * 8) = y1; *(LAS h8*)(Ks + pos * KSTR + 64 + ch * 8) = y2; }
; #pragma unroll
;     for (int i = 0; i < 8; ++i) { const int id = tid + 512 * i, pos = id >> 5, ch = id & 31;
;         *(LAS h8*)(Vs + pos * VSTR + ch * 8) = *(const h8*)(PR + (size_t)(tb + pos) * NIN + C_RV + h * 256 + ch * 8); }
	v_lshl_add_u64 v[192:193], v[192:193], 0, s[20:21]
	v_add_u32_e32 v200, s10, v71
	v_lshl_add_u64 v[196:197], v[192:193], 0, v[84:85]
	v_ashrrev_i32_e32 v201, 31, v200
	global_load_dwordx4 v[192:195], v[196:197], off offset:2048
	s_nop 0
	global_load_dwordx4 v[196:199], v[196:197], off offset:2176
	v_lshlrev_b64 v[200:201], 8, v[200:201]
	v_lshl_add_u64 v[208:209], v[68:69], 0, v[200:201]
	v_lshl_add_u64 v[212:213], v[208:209], 0, s[14:15]
	global_load_dwordx4 v[200:203], v[208:209], off offset:16
	global_load_dwordx4 v[204:207], v[208:209], off
	v_add_co_u32_e32 v208, vcc, s11, v208
	s_lshl_b32 s20, s5, 9
	s_nop 0
	v_addc_co_u32_e32 v209, vcc, 0, v209, vcc
	global_load_dwordx4 v[208:211], v[208:209], off
	s_nop 0
	global_load_dwordx4 v[212:215], v[212:213], off offset:16
	v_add_u32_e32 v244, s1, v73
	v_mad_i64_i32 v[248:249], s[12:13], v244, s35, v[0:1]
	v_lshl_add_u64 v[248:249], v[248:249], 0, s[20:21]
	v_lshl_add_u64 v[248:249], v[248:249], 0, v[86:87]
	v_add_co_u32_e32 v248, vcc, s33, v248
	s_nop 1
	v_addc_co_u32_e32 v249, vcc, 0, v249, vcc
	global_load_dwordx4 v[216:219], v[248:249], off
	v_add_u32_e32 v244, s1, v92
	v_mad_i64_i32 v[248:249], s[12:13], v244, s35, v[0:1]
	v_lshl_add_u64 v[248:249], v[248:249], 0, s[20:21]
	v_lshl_add_u64 v[248:249], v[248:249], 0, v[86:87]
	v_add_co_u32_e32 v248, vcc, s33, v248
	s_nop 1
	v_addc_co_u32_e32 v249, vcc, 0, v249, vcc
	global_load_dwordx4 v[220:223], v[248:249], off
	v_add_u32_e32 v244, s1, v93
	v_mad_i64_i32 v[248:249], s[12:13], v244, s35, v[0:1]
	v_lshl_add_u64 v[248:249], v[248:249], 0, s[20:21]
	v_lshl_add_u64 v[248:249], v[248:249], 0, v[86:87]
	v_add_co_u32_e32 v248, vcc, s33, v248
	s_nop 1
	v_addc_co_u32_e32 v249, vcc, 0, v249, vcc
	global_load_dwordx4 v[224:227], v[248:249], off
	v_add_u32_e32 v244, s1, v94
	v_mad_i64_i32 v[248:249], s[12:13], v244, s35, v[0:1]
	v_lshl_add_u64 v[248:249], v[248:249], 0, s[20:21]
	v_lshl_add_u64 v[248:249], v[248:249], 0, v[86:87]
	v_add_co_u32_e32 v248, vcc, s33, v248
	s_nop 1
	v_addc_co_u32_e32 v249, vcc, 0, v249, vcc
	global_load_dwordx4 v[228:231], v[248:249], off
	v_add_u32_e32 v244, s1, v95
	v_mad_i64_i32 v[248:249], s[12:13], v244, s35, v[0:1]
	v_lshl_add_u64 v[248:249], v[248:249], 0, s[20:21]
	v_lshl_add_u64 v[248:249], v[248:249], 0, v[86:87]
	v_add_co_u32_e32 v248, vcc, s33, v248
	s_nop 1
	v_addc_co_u32_e32 v249, vcc, 0, v249, vcc
	global_load_dwordx4 v[232:235], v[248:249], off
	v_add_u32_e32 v244, s1, v96
	v_mad_i64_i32 v[248:249], s[12:13], v244, s35, v[0:1]
	v_lshl_add_u64 v[248:249], v[248:249], 0, s[20:21]
	v_lshl_add_u64 v[248:249], v[248:249], 0, v[86:87]
	v_add_co_u32_e32 v248, vcc, s33, v248
	s_nop 1
	v_addc_co_u32_e32 v249, vcc, 0, v249, vcc
	global_load_dwordx4 v[236:239], v[248:249], off
	v_add_u32_e32 v244, s1, v97
	v_mad_i64_i32 v[248:249], s[12:13], v244, s35, v[0:1]
	v_lshl_add_u64 v[248:249], v[248:249], 0, s[20:21]
	v_lshl_add_u64 v[248:249], v[248:249], 0, v[86:87]
	v_add_co_u32_e32 v248, vcc, s33, v248
	s_nop 1
	v_addc_co_u32_e32 v249, vcc, 0, v249, vcc
	global_load_dwordx4 v[240:243], v[248:249], off
	v_add_u32_e32 v244, s1, v98
	v_mad_i64_i32 v[248:249], s[12:13], v244, s35, v[0:1]
	v_lshl_add_u64 v[248:249], v[248:249], 0, s[20:21]
	v_lshl_add_u64 v[248:249], v[248:249], 0, v[86:87]
	v_add_co_u32_e32 v248, vcc, s33, v248
	s_nop 1
	v_addc_co_u32_e32 v249, vcc, 0, v249, vcc
	global_load_dwordx4 v[244:247], v[248:249], off
	s_waitcnt vmcnt(19)
	v_cvt_f32_f16_e32 v30, v8
	v_cvt_f32_f16_sdwa v31, v8 dst_sel:DWORD dst_unused:UNUSED_PAD src0_sel:WORD_1
	s_waitcnt vmcnt(18)
	v_cvt_f32_f16_e32 v32, v4
	v_cvt_f32_f16_sdwa v33, v4 dst_sel:DWORD dst_unused:UNUSED_PAD src0_sel:WORD_1
	s_waitcnt vmcnt(15)
	v_pk_mul_f32 v[34:35], v[20:21], v[30:31]
	v_pk_mul_f32 v[20:21], v[20:21], v[32:33]
	v_pk_fma_f32 v[34:35], v[16:17], v[32:33], v[34:35]
	v_pk_fma_f32 v[16:17], v[16:17], v[30:31], v[20:21] neg_lo:[0,0,1] neg_hi:[0,0,1]
	v_cvt_f32_f16_e32 v20, v5
	v_pk_mul_f32 v[16:17], v[28:29], v[16:17] op_sel_hi:[0,1]
	v_cvt_pk_f16_f32 v8, v16, v17
	v_cvt_f32_f16_e32 v16, v9
	v_cvt_f32_f16_sdwa v17, v9 dst_sel:DWORD dst_unused:UNUSED_PAD src0_sel:WORD_1
	v_cvt_f32_f16_sdwa v21, v5 dst_sel:DWORD dst_unused:UNUSED_PAD src0_sel:WORD_1
	v_pk_mul_f32 v[34:35], v[28:29], v[34:35] op_sel_hi:[0,1]
	v_cvt_pk_f16_f32 v4, v34, v35
	v_pk_mul_f32 v[30:31], v[22:23], v[16:17]
	s_nop 0
	v_pk_fma_f32 v[30:31], v[18:19], v[20:21], v[30:31]
	v_pk_mul_f32 v[20:21], v[22:23], v[20:21]
	v_pk_mul_f32 v[30:31], v[28:29], v[30:31] op_sel_hi:[0,1]
	v_pk_fma_f32 v[16:17], v[18:19], v[16:17], v[20:21] neg_lo:[0,0,1] neg_hi:[0,0,1]
	v_cvt_f32_f16_e32 v18, v6
	v_pk_mul_f32 v[16:17], v[28:29], v[16:17] op_sel_hi:[0,1]
	v_cvt_pk_f16_f32 v9, v16, v17
	v_cvt_f32_f16_e32 v16, v10
	v_cvt_f32_f16_sdwa v17, v10 dst_sel:DWORD dst_unused:UNUSED_PAD src0_sel:WORD_1
	v_cvt_f32_f16_sdwa v19, v6 dst_sel:DWORD dst_unused:UNUSED_PAD src0_sel:WORD_1
	v_cvt_pk_f16_f32 v5, v30, v31
	s_waitcnt vmcnt(14)
; #define LAS __attribute__((address_space(3)))
; __device__ __forceinline__ h4 tr_read(const LAS half_t* p) { s4v r = __builtin_amdgcn_ds_read_tr16_b64_v4i16((LAS s4v*)p); return __builtin_bit_cast(h4, r); }
; __device__ __forceinline__ float ret_logg(int h) { return log1pf(-exp2f(-5.f - (float)h)); }
; template <bool ZETA>
; __device__ __forceinline__ void ret_stage(const Params& p, LAS unsigned char* lds, int tb, int h, int c, float logg, int tid) {
;     ...
;         h8 y1, y2;
; #pragma unroll
;         for (int e = 0; e < 8; ++e) { const float co = e < 4 ? c0[e & 3] : c1[e & 3], si = e < 4 ? s0[e & 3] : s1[e & 3]; const float a = (float)x1[e], b = (float)x2[e];
;             y1[e] = (half_t)((a * co - b * si) * sc); y2[e] = (half_t)((b * co + a * si) * sc); }
;         *(LAS h8*)(Ks + pos * KSTR + ch * 8) = y1; *(LAS h8*)(Ks + pos * KSTR + 64 + ch * 8) = y2; }
; #pragma unroll
;     for (int i = 0; i < 8; ++i) { const int id = tid + 512 * i, pos = id >> 5, ch = id & 31;
;         *(LAS h8*)(Vs + pos * VSTR + ch * 8) = *(const h8*)(PR + (size_t)(tb + pos) * NIN + C_RV + h * 256 + ch * 8); }
; }
; __device__ __forceinline__ void ret_kv_item(const Params& p, LAS unsigned char* lds, int item, int tid, int wave, int lane) {
;     const int b = item >> 8, h = (item >> 5) & 7, c = item & 31, tb = b * SEQ + c * 128;
;     const float logg = ret_logg(h);
;     ret_stage<true>(p, lds, tb, h, c, logg, tid);
;     __syncthreads();
;     const LAS half_t* Ks = (const LAS half_t*)lds; const LAS half_t* Vs = (const LAS half_t*)(lds + RV_OFF);
;     const int g = lane >> 4, r = lane & 15, q = (lane & 15) >> 2, pp = lane & 3;
;     h8 a[4];
; #pragma unroll
;     for (int ks = 0; ks < 4; ++ks) { const LAS half_t* ap = Ks + (ks * 32 + g * 8 + q) * KSTR + wave * 16 + 4 * pp; a[ks] = cat8(tr_read(ap), tr_read(ap + 4 * KSTR)); }
	v_pk_mul_f32 v[20:21], v[24:25], v[16:17]
	s_nop 0
	v_pk_fma_f32 v[20:21], v[12:13], v[18:19], v[20:21]
	v_pk_mul_f32 v[18:19], v[24:25], v[18:19]
	v_pk_mul_f32 v[20:21], v[28:29], v[20:21] op_sel_hi:[0,1]
	v_pk_fma_f32 v[12:13], v[12:13], v[16:17], v[18:19] neg_lo:[0,0,1] neg_hi:[0,0,1]
	v_cvt_f32_f16_e32 v16, v7
	v_pk_mul_f32 v[12:13], v[28:29], v[12:13] op_sel_hi:[0,1]
	v_cvt_pk_f16_f32 v10, v12, v13
	v_cvt_f32_f16_e32 v12, v11
	v_cvt_f32_f16_sdwa v13, v11 dst_sel:DWORD dst_unused:UNUSED_PAD src0_sel:WORD_1
	v_cvt_f32_f16_sdwa v17, v7 dst_sel:DWORD dst_unused:UNUSED_PAD src0_sel:WORD_1
	v_cvt_pk_f16_f32 v6, v20, v21
	v_pk_mul_f32 v[18:19], v[26:27], v[12:13]
	s_nop 0
	v_pk_fma_f32 v[18:19], v[14:15], v[16:17], v[18:19]
	v_pk_mul_f32 v[16:17], v[26:27], v[16:17]
	v_pk_mul_f32 v[18:19], v[28:29], v[18:19] op_sel_hi:[0,1]
	v_pk_fma_f32 v[12:13], v[14:15], v[12:13], v[16:17] neg_lo:[0,0,1] neg_hi:[0,0,1]
	v_cvt_pk_f16_f32 v7, v18, v19
	v_pk_mul_f32 v[12:13], v[28:29], v[12:13] op_sel_hi:[0,1]
	v_cvt_pk_f16_f32 v11, v12, v13
	ds_write_b128 v70, v[8:11]
	ds_write_b128 v70, v[4:7] offset:128
	s_add_u32 s0, s18, s0
	s_waitcnt vmcnt(13)
	v_cvt_f32_f16_e32 v30, v192
	v_cvt_f32_f16_sdwa v31, v192 dst_sel:DWORD dst_unused:UNUSED_PAD src0_sel:WORD_1
	s_waitcnt vmcnt(12)
	v_cvt_f32_f16_e32 v28, v196
	v_cvt_f32_f16_sdwa v29, v196 dst_sel:DWORD dst_unused:UNUSED_PAD src0_sel:WORD_1
	v_cvt_f32_f16_e32 v34, v193
	v_cvt_f32_f16_sdwa v35, v193 dst_sel:DWORD dst_unused:UNUSED_PAD src0_sel:WORD_1
	v_cvt_f32_f16_e32 v38, v194
	v_cvt_f32_f16_sdwa v39, v194 dst_sel:DWORD dst_unused:UNUSED_PAD src0_sel:WORD_1
	v_cvt_f32_f16_e32 v36, v198
	v_cvt_f32_f16_sdwa v37, v198 dst_sel:DWORD dst_unused:UNUSED_PAD src0_sel:WORD_1
	s_waitcnt vmcnt(9)
	v_pk_mul_f32 v[32:33], v[208:209], v[30:31]
	s_nop 0
	v_pk_fma_f32 v[32:33], v[204:205], v[28:29], v[32:33]
	s_nop 0
	v_pk_mul_f32 v[32:33], v[2:3], v[32:33] op_sel_hi:[0,1]
	v_cvt_pk_f16_f32 v192, v32, v33
	v_cvt_f32_f16_e32 v32, v197
	v_cvt_f32_f16_sdwa v33, v197 dst_sel:DWORD dst_unused:UNUSED_PAD src0_sel:WORD_1
	v_pk_mul_f32 v[196:197], v[210:211], v[34:35]
	s_nop 0
	v_pk_fma_f32 v[196:197], v[206:207], v[32:33], v[196:197]
	s_nop 0
	v_pk_mul_f32 v[196:197], v[2:3], v[196:197] op_sel_hi:[0,1]
	v_cvt_pk_f16_f32 v193, v196, v197
	s_waitcnt vmcnt(8)
	v_pk_mul_f32 v[196:197], v[212:213], v[38:39]
	s_nop 0
	v_pk_fma_f32 v[196:197], v[200:201], v[36:37], v[196:197]
	s_nop 0
	v_pk_mul_f32 v[196:197], v[2:3], v[196:197] op_sel_hi:[0,1]
	v_cvt_pk_f16_f32 v194, v196, v197
	v_pk_mul_f32 v[196:197], v[208:209], v[28:29]
	s_nop 0
	v_pk_fma_f32 v[196:197], v[204:205], v[30:31], v[196:197] neg_lo:[0,0,1] neg_hi:[0,0,1]
	v_pk_mul_f32 v[204:205], v[210:211], v[32:33]
	v_pk_mul_f32 v[196:197], v[2:3], v[196:197] op_sel_hi:[0,1]
	v_pk_fma_f32 v[204:205], v[206:207], v[34:35], v[204:205] neg_lo:[0,0,1] neg_hi:[0,0,1]
	v_cvt_pk_f16_f32 v196, v196, v197
	v_pk_mul_f32 v[204:205], v[2:3], v[204:205] op_sel_hi:[0,1]
	v_cvt_pk_f16_f32 v197, v204, v205
	v_pk_mul_f32 v[204:205], v[212:213], v[36:37]
	s_nop 0
	v_pk_fma_f32 v[200:201], v[200:201], v[38:39], v[204:205] neg_lo:[0,0,1] neg_hi:[0,0,1]
	v_cvt_f32_f16_e32 v204, v199
	v_pk_mul_f32 v[200:201], v[2:3], v[200:201] op_sel_hi:[0,1]
	v_cvt_pk_f16_f32 v198, v200, v201
	v_cvt_f32_f16_e32 v200, v195
	v_cvt_f32_f16_sdwa v201, v195 dst_sel:DWORD dst_unused:UNUSED_PAD src0_sel:WORD_1
	v_cvt_f32_f16_sdwa v205, v199 dst_sel:DWORD dst_unused:UNUSED_PAD src0_sel:WORD_1
	v_pk_mul_f32 v[206:207], v[214:215], v[200:201]
	s_nop 0
	v_pk_fma_f32 v[206:207], v[202:203], v[204:205], v[206:207]
	v_pk_mul_f32 v[204:205], v[214:215], v[204:205]
	v_pk_mul_f32 v[206:207], v[2:3], v[206:207] op_sel_hi:[0,1]
	v_pk_fma_f32 v[200:201], v[202:203], v[200:201], v[204:205] neg_lo:[0,0,1] neg_hi:[0,0,1]
	v_cvt_pk_f16_f32 v195, v206, v207
	v_pk_mul_f32 v[200:201], v[2:3], v[200:201] op_sel_hi:[0,1]
	v_cvt_pk_f16_f32 v199, v200, v201
	ds_write_b128 v72, v[196:199]
	ds_write_b128 v72, v[192:195] offset:128
	s_waitcnt vmcnt(7)
	ds_write_b128 v118, v[216:219] offset:34816
	s_waitcnt vmcnt(6)
	ds_write_b128 v119, v[220:223] offset:34816
	s_waitcnt vmcnt(5)
	ds_write_b128 v120, v[224:227] offset:34816
	s_waitcnt vmcnt(4)
	ds_write_b128 v121, v[228:231] offset:34816
	s_waitcnt vmcnt(3)
	ds_write_b128 v122, v[232:235] offset:34816
	s_waitcnt vmcnt(2)
	ds_write_b128 v123, v[236:239] offset:34816
	s_waitcnt vmcnt(1)
	ds_write_b128 v124, v[240:243] offset:34816
	s_waitcnt vmcnt(0)
	ds_write_b128 v125, v[244:247] offset:34816
	s_addc_u32 s1, s19, 0
	v_mov_b32_e32 v0, v117
	s_waitcnt lgkmcnt(0)
	s_barrier
	ds_read_b64_tr_b16 v[4:5], v126
	ds_read_b64_tr_b16 v[6:7], v126 offset:1088
	ds_read_b64_tr_b16 v[8:9], v126 offset:8704
	ds_read_b64_tr_b16 v[10:11], v126 offset:9792
	ds_read_b64_tr_b16 v[12:13], v126 offset:17408
	ds_read_b64_tr_b16 v[14:15], v126 offset:18496
	ds_read_b64_tr_b16 v[16:17], v126 offset:26112
	ds_read_b64_tr_b16 v[18:19], v126 offset:27200

; __device__ __forceinline__ float ex2(float x) { return __builtin_amdgcn_exp2f(x); }
;     __device__ __forceinline__ void operator()(const f32x4 (&acc)[2][2][4][2], const pg8::Unit& u, int wr, int wc, int fr, int fq) const {
;         const int row0 = u.pm * 256 + wr * 64 + fr, col0 = u.pn * 256 + wc * 32 + 8 * fq;
; #pragma unroll
;         for (int ai = 0; ai < 2; ++ai)
; #pragma unroll
;             for (int m = 0; m < 4; ++m) { const size_t row = (size_t)(row0 + ai * 128 + m * 16);
; #pragma unroll
;                 for (int bj = 0; bj < 2; ++bj) { const h8 gb = *(const h8*)(P + row * NIN + col0 + C_MS + bj * 128);
;                     h8 o;
; #pragma unroll
;                     for (int n = 0; n < 2; ++n)
; #pragma unroll
;                         for (int i = 0; i < 4; ++i) o[4 * n + i] = op16(acc[ai][bj][m][n][i] * __builtin_amdgcn_rcpf(1.f + ex2((float)gb[4 * n + i] * -1.44269504f)), TAIL_BF16);
;                     *(h8*)(O + row * DM + col0 + bj * 128) = o; } }
;     }
.LBB0_586:
	v_ashrrev_i32_e32 v169, 31, v168
	v_mov_b64_e32 v[132:133], s[36:37]
	v_mad_i64_i32 v[136:137], s[10:11], v166, s35, v[132:133]
	v_lshlrev_b64 v[0:1], 1, v[168:169]
	v_lshl_add_u64 v[136:137], v[136:137], 0, v[0:1]
	v_add_co_u32_e32 v136, vcc, 0x6000, v136
	v_ashrrev_i32_e32 v167, 31, v166
	s_nop 0
	v_addc_co_u32_e32 v137, vcc, 0, v137, vcc
	v_add_co_u32_e32 v248, vcc, 0, v136
	s_nop 1
	v_addc_co_u32_e32 v249, vcc, 0, v137, vcc
	global_load_dwordx4 v[192:195], v[248:249], off offset:2048
	v_add_co_u32_e32 v248, vcc, 0, v136
	s_nop 1
	v_addc_co_u32_e32 v249, vcc, 0, v137, vcc
	global_load_dwordx4 v[196:199], v[248:249], off offset:2304
	v_add_co_u32_e32 v248, vcc, 0x78000, v136
	s_nop 1
	v_addc_co_u32_e32 v249, vcc, 0, v137, vcc
	global_load_dwordx4 v[200:203], v[248:249], off offset:2048
	v_add_co_u32_e32 v248, vcc, 0x78000, v136
	s_nop 1
	v_addc_co_u32_e32 v249, vcc, 0, v137, vcc
	global_load_dwordx4 v[204:207], v[248:249], off offset:2304
	v_add_co_u32_e32 v248, vcc, 0xf0000, v136
	s_nop 1
	v_addc_co_u32_e32 v249, vcc, 0, v137, vcc
	global_load_dwordx4 v[208:211], v[248:249], off offset:2048
	v_add_co_u32_e32 v248, vcc, 0xf0000, v136
	s_nop 1
	v_addc_co_u32_e32 v249, vcc, 0, v137, vcc
	global_load_dwordx4 v[212:215], v[248:249], off offset:2304
	v_add_co_u32_e32 v248, vcc, 0x168000, v136
	s_nop 1
	v_addc_co_u32_e32 v249, vcc, 0, v137, vcc
	global_load_dwordx4 v[216:219], v[248:249], off offset:2048
	v_add_co_u32_e32 v248, vcc, 0x168000, v136
	s_nop 1
	v_addc_co_u32_e32 v249, vcc, 0, v137, vcc
	global_load_dwordx4 v[220:223], v[248:249], off offset:2304
	v_add_co_u32_e32 v248, vcc, 0x3c0000, v136
	s_nop 1
	v_addc_co_u32_e32 v249, vcc, 0, v137, vcc
	global_load_dwordx4 v[224:227], v[248:249], off offset:2048
	v_add_co_u32_e32 v248, vcc, 0x3c0000, v136
	s_nop 1
	v_addc_co_u32_e32 v249, vcc, 0, v137, vcc
	global_load_dwordx4 v[228:231], v[248:249], off offset:2304
	v_add_co_u32_e32 v248, vcc, 0x438000, v136
	s_nop 1
	v_addc_co_u32_e32 v249, vcc, 0, v137, vcc
	global_load_dwordx4 v[232:235], v[248:249], off offset:2048
	v_add_co_u32_e32 v248, vcc, 0x438000, v136
	s_nop 1
	v_addc_co_u32_e32 v249, vcc, 0, v137, vcc
	global_load_dwordx4 v[236:239], v[248:249], off offset:2304
	v_add_co_u32_e32 v248, vcc, 0x4b0000, v136
	s_nop 1
	v_addc_co_u32_e32 v249, vcc, 0, v137, vcc
	global_load_dwordx4 v[240:243], v[248:249], off offset:2048
	v_add_co_u32_e32 v248, vcc, 0x4b0000, v136
	s_nop 1
	v_addc_co_u32_e32 v249, vcc, 0, v137, vcc
	global_load_dwordx4 v[244:247], v[248:249], off offset:2304
	v_add_co_u32_e32 v248, vcc, 0x528000, v136
	s_nop 1
	v_addc_co_u32_e32 v249, vcc, 0, v137, vcc
	global_load_dwordx4 v[172:175], v[248:249], off offset:2048
	v_add_co_u32_e32 v248, vcc, 0x528000, v136
	s_nop 1
	v_addc_co_u32_e32 v249, vcc, 0, v137, vcc
	global_load_dwordx4 v[176:179], v[248:249], off offset:2304
	s_nop 1
	s_waitcnt vmcnt(15)
	v_mov_b32_e32 v168, v192
	v_mov_b32_e32 v169, v193
	v_mov_b32_e32 v170, v194
	v_mov_b32_e32 v171, v195
	v_lshlrev_b64 v[134:135], 12, v[166:167]
	s_movk_i32 s1, 0x6000
	s_movk_i32 s61, 0x6000
	s_mov_b32 s14, s0
	s_mov_b32 s15, s4
	s_mov_b64 s[12:13], s[8:9]
	s_nop 0
	v_cvt_f32_f16_e32 v2, v168
	v_mul_f32_e32 v2, 0xbfb8aa3b, v2
	v_exp_f32_e32 v2, v2
	s_nop 0
	v_add_f32_e32 v2, 1.0, v2
	v_rcp_f32_e32 v2, v2
	s_nop 0
	v_mul_f32_e32 v2, v128, v2
	v_cvt_f32_f16_sdwa v128, v168 dst_sel:DWORD dst_unused:UNUSED_PAD src0_sel:WORD_1
	v_cvt_pk_bf16_f32 v2, v2, s0
	v_mul_f32_e32 v128, 0xbfb8aa3b, v128
	v_exp_f32_e32 v128, v128
	s_nop 0
	v_add_f32_e32 v128, 1.0, v128
	v_rcp_f32_e32 v138, v128
	v_cvt_f32_f16_e32 v128, v169
	v_mul_f32_e32 v128, 0xbfb8aa3b, v128
	v_exp_f32_e32 v128, v128
	s_nop 0
	v_add_f32_e32 v128, 1.0, v128
	v_rcp_f32_e32 v139, v128
	v_mov_b32_e32 v128, v129
	v_mov_b32_e32 v129, v130
	v_pk_mov_b32 v[130:131], v[130:131], v[124:125] op_sel:[1,0]
	v_pk_mul_f32 v[128:129], v[128:129], v[138:139]
	v_cvt_f32_f16_sdwa v124, v170 dst_sel:DWORD dst_unused:UNUSED_PAD src0_sel:WORD_1
	v_cvt_pk_bf16_f32 v129, v128, v129
	v_perm_b32 v128, v129, v2, s45
	v_cvt_f32_f16_sdwa v2, v169 dst_sel:DWORD dst_unused:UNUSED_PAD src0_sel:WORD_1
	v_mul_f32_e32 v124, 0xbfb8aa3b, v124
	v_exp_f32_e32 v124, v124
	v_mul_f32_e32 v2, 0xbfb8aa3b, v2
	v_exp_f32_e32 v2, v2
	v_add_f32_e32 v124, 1.0, v124
	v_add_f32_e32 v2, 1.0, v2
	v_rcp_f32_e32 v138, v2
	v_cvt_f32_f16_e32 v2, v170
	v_mul_f32_e32 v2, 0xbfb8aa3b, v2
	v_exp_f32_e32 v2, v2
	s_nop 0
	v_add_f32_e32 v2, 1.0, v2
	v_rcp_f32_e32 v139, v2
	s_nop 0
	v_pk_mul_f32 v[130:131], v[130:131], v[138:139]
	s_nop 0
	v_cvt_pk_bf16_f32 v2, v130, v131
	v_rcp_f32_e32 v130, v124
	v_cvt_f32_f16_e32 v124, v171
	v_alignbit_b32 v129, v2, v129, 16
	v_mul_f32_e32 v124, 0xbfb8aa3b, v124
	v_exp_f32_e32 v124, v124
	s_nop 0
	v_add_f32_e32 v124, 1.0, v124
	v_rcp_f32_e32 v131, v124
	v_mov_b32_e32 v124, v125
	v_mov_b32_e32 v125, v126
	v_pk_mul_f32 v[124:125], v[124:125], v[130:131]
	s_nop 0
	v_cvt_pk_bf16_f32 v124, v124, v125
	v_alignbit_b32 v130, v124, v2, 16
	v_cvt_f32_f16_sdwa v2, v171 dst_sel:DWORD dst_unused:UNUSED_PAD src0_sel:WORD_1
	v_mul_f32_e32 v2, 0xbfb8aa3b, v2
	v_exp_f32_e32 v2, v2
	s_nop 0
	v_add_f32_e32 v2, 1.0, v2
	v_rcp_f32_e32 v2, v2
	s_nop 0
	v_mul_f32_e32 v2, v127, v2
	v_cvt_pk_bf16_f32 v2, v2, s0
	v_alignbit_b32 v131, v2, v124, 16
	v_lshl_add_u64 v[124:125], s[26:27], 0, v[134:135]
	v_lshl_add_u64 v[134:135], v[124:125], 0, v[0:1]
	s_nop 1
	s_waitcnt vmcnt(14)
; __device__ __forceinline__ float ex2(float x) { return __builtin_amdgcn_exp2f(x); }
;     __device__ __forceinline__ void operator()(const f32x4 (&acc)[2][2][4][2], const pg8::Unit& u, int wr, int wc, int fr, int fq) const {
;         const int row0 = u.pm * 256 + wr * 64 + fr, col0 = u.pn * 256 + wc * 32 + 8 * fq;
; #pragma unroll
;         for (int ai = 0; ai < 2; ++ai)
; #pragma unroll
;             for (int m = 0; m < 4; ++m) { const size_t row = (size_t)(row0 + ai * 128 + m * 16);
; #pragma unroll
;                 for (int bj = 0; bj < 2; ++bj) { const h8 gb = *(const h8*)(P + row * NIN + col0 + C_MS + bj * 128);
;                     h8 o;
; #pragma unroll
;                     for (int n = 0; n < 2; ++n)
; #pragma unroll
;                         for (int i = 0; i < 4; ++i) o[4 * n + i] = op16(acc[ai][bj][m][n][i] * __builtin_amdgcn_rcpf(1.f + ex2((float)gb[4 * n + i] * -1.44269504f)), TAIL_BF16);
;                     *(h8*)(O + row * DM + col0 + bj * 128) = o; } }
;     }
	v_mov_b32_e32 v124, v196
	v_mov_b32_e32 v125, v197
	v_mov_b32_e32 v126, v198
	v_mov_b32_e32 v127, v199
	s_nop 0
	v_cvt_f32_f16_e32 v2, v124
	global_store_dwordx4 v[134:135], v[128:131], off
	v_mul_f32_e32 v2, 0xbfb8aa3b, v2
	v_exp_f32_e32 v2, v2
	s_nop 0
	v_add_f32_e32 v2, 1.0, v2
	v_rcp_f32_e32 v2, v2
	s_nop 0
	v_mul_f32_e32 v2, v120, v2
	v_cvt_f32_f16_sdwa v120, v124 dst_sel:DWORD dst_unused:UNUSED_PAD src0_sel:WORD_1
	v_cvt_pk_bf16_f32 v2, v2, s0
	v_mul_f32_e32 v120, 0xbfb8aa3b, v120
	v_exp_f32_e32 v120, v120
	s_nop 0
	v_add_f32_e32 v120, 1.0, v120
	v_rcp_f32_e32 v128, v120
	v_cvt_f32_f16_e32 v120, v125
	v_mul_f32_e32 v120, 0xbfb8aa3b, v120
	v_exp_f32_e32 v120, v120
	s_nop 0
	v_add_f32_e32 v120, 1.0, v120
	v_rcp_f32_e32 v129, v120
	v_mov_b32_e32 v120, v121
	v_mov_b32_e32 v121, v122
	v_pk_mov_b32 v[122:123], v[122:123], v[116:117] op_sel:[1,0]
	v_pk_mul_f32 v[120:121], v[120:121], v[128:129]
	v_cvt_f32_f16_sdwa v116, v126 dst_sel:DWORD dst_unused:UNUSED_PAD src0_sel:WORD_1
	v_cvt_pk_bf16_f32 v121, v120, v121
	v_perm_b32 v120, v121, v2, s45
	v_cvt_f32_f16_sdwa v2, v125 dst_sel:DWORD dst_unused:UNUSED_PAD src0_sel:WORD_1
	v_mul_f32_e32 v116, 0xbfb8aa3b, v116
	v_exp_f32_e32 v116, v116
	v_mul_f32_e32 v2, 0xbfb8aa3b, v2
	v_exp_f32_e32 v2, v2
	v_add_f32_e32 v116, 1.0, v116
	v_add_f32_e32 v2, 1.0, v2
	v_rcp_f32_e32 v124, v2
	v_cvt_f32_f16_e32 v2, v126
	v_mul_f32_e32 v2, 0xbfb8aa3b, v2
	v_exp_f32_e32 v2, v2
	s_nop 0
	v_add_f32_e32 v2, 1.0, v2
	v_rcp_f32_e32 v125, v2
	s_nop 0
	v_pk_mul_f32 v[122:123], v[122:123], v[124:125]
	s_nop 0
	v_cvt_pk_bf16_f32 v2, v122, v123
	v_rcp_f32_e32 v122, v116
	v_cvt_f32_f16_e32 v116, v127
	v_alignbit_b32 v121, v2, v121, 16
	v_mul_f32_e32 v116, 0xbfb8aa3b, v116
	v_exp_f32_e32 v116, v116
	s_nop 0
	v_add_f32_e32 v116, 1.0, v116
	v_rcp_f32_e32 v123, v116
	v_mov_b32_e32 v116, v117
	v_mov_b32_e32 v117, v118
	v_pk_mul_f32 v[116:117], v[116:117], v[122:123]
	s_nop 0
	v_cvt_pk_bf16_f32 v116, v116, v117
	v_alignbit_b32 v122, v116, v2, 16
	v_cvt_f32_f16_sdwa v2, v127 dst_sel:DWORD dst_unused:UNUSED_PAD src0_sel:WORD_1
	v_mul_f32_e32 v2, 0xbfb8aa3b, v2
	v_exp_f32_e32 v2, v2
	s_nop 0
	v_add_f32_e32 v2, 1.0, v2
	v_rcp_f32_e32 v2, v2
	s_nop 0
	v_mul_f32_e32 v2, v119, v2
	v_cvt_pk_bf16_f32 v2, v2, s0
	v_alignbit_b32 v123, v2, v116, 16
	v_or_b32_e32 v116, 16, v166
	v_ashrrev_i32_e32 v117, 31, v116
	global_store_dwordx4 v[134:135], v[120:123], off offset:256
	s_nop 1
	v_lshlrev_b64 v[122:123], 12, v[116:117]
	v_mad_i64_i32 v[116:117], s[10:11], v116, s35, v[132:133]
	v_lshl_add_u64 v[116:117], v[116:117], 0, v[0:1]
	v_add_co_u32_e32 v120, vcc, s1, v116
	s_nop 1
	v_addc_co_u32_e32 v121, vcc, 0, v117, vcc
	s_nop 1
	s_waitcnt vmcnt(13)
	v_mov_b32_e32 v116, v200
	v_mov_b32_e32 v117, v201
	v_mov_b32_e32 v118, v202
	v_mov_b32_e32 v119, v203
	s_nop 0
	v_cvt_f32_f16_e32 v2, v116
	v_mul_f32_e32 v2, 0xbfb8aa3b, v2
	v_exp_f32_e32 v2, v2
	s_nop 0
	v_add_f32_e32 v2, 1.0, v2
	v_rcp_f32_e32 v2, v2
	s_nop 0
	v_mul_f32_e32 v2, v112, v2
	v_cvt_f32_f16_sdwa v112, v116 dst_sel:DWORD dst_unused:UNUSED_PAD src0_sel:WORD_1
	v_cvt_pk_bf16_f32 v2, v2, s0
	v_mul_f32_e32 v112, 0xbfb8aa3b, v112
	v_exp_f32_e32 v112, v112
	s_nop 0
	v_add_f32_e32 v112, 1.0, v112
	v_rcp_f32_e32 v124, v112
	v_cvt_f32_f16_e32 v112, v117
	v_mul_f32_e32 v112, 0xbfb8aa3b, v112
	v_exp_f32_e32 v112, v112
	s_nop 0
	v_add_f32_e32 v112, 1.0, v112
	v_rcp_f32_e32 v125, v112
	v_mov_b32_e32 v112, v113
	v_mov_b32_e32 v113, v114
	v_pk_mov_b32 v[114:115], v[114:115], v[108:109] op_sel:[1,0]
	v_pk_mul_f32 v[112:113], v[112:113], v[124:125]
	v_cvt_f32_f16_sdwa v108, v118 dst_sel:DWORD dst_unused:UNUSED_PAD src0_sel:WORD_1
	v_cvt_pk_bf16_f32 v113, v112, v113
	v_perm_b32 v112, v113, v2, s45
	v_cvt_f32_f16_sdwa v2, v117 dst_sel:DWORD dst_unused:UNUSED_PAD src0_sel:WORD_1
	v_mul_f32_e32 v108, 0xbfb8aa3b, v108
	v_exp_f32_e32 v108, v108
	v_mul_f32_e32 v2, 0xbfb8aa3b, v2
	v_exp_f32_e32 v2, v2
	v_add_f32_e32 v108, 1.0, v108
	v_add_f32_e32 v2, 1.0, v2
	v_rcp_f32_e32 v116, v2
	v_cvt_f32_f16_e32 v2, v118
	v_mul_f32_e32 v2, 0xbfb8aa3b, v2
	v_exp_f32_e32 v2, v2
	s_nop 0
	v_add_f32_e32 v2, 1.0, v2
	v_rcp_f32_e32 v117, v2
	s_nop 0
	v_pk_mul_f32 v[114:115], v[114:115], v[116:117]
	s_nop 0
	v_cvt_pk_bf16_f32 v2, v114, v115
	v_rcp_f32_e32 v114, v108
	v_cvt_f32_f16_e32 v108, v119
	v_alignbit_b32 v113, v2, v113, 16
	v_mul_f32_e32 v108, 0xbfb8aa3b, v108
	v_exp_f32_e32 v108, v108
	s_nop 0
	v_add_f32_e32 v108, 1.0, v108
	v_rcp_f32_e32 v115, v108
	v_mov_b32_e32 v108, v109
	v_mov_b32_e32 v109, v110
	v_pk_mul_f32 v[108:109], v[108:109], v[114:115]
	s_nop 0
	v_cvt_pk_bf16_f32 v108, v108, v109
	v_alignbit_b32 v114, v108, v2, 16
	v_cvt_f32_f16_sdwa v2, v119 dst_sel:DWORD dst_unused:UNUSED_PAD src0_sel:WORD_1
	v_mul_f32_e32 v2, 0xbfb8aa3b, v2
	v_exp_f32_e32 v2, v2
	s_nop 0
	v_add_f32_e32 v2, 1.0, v2
	v_rcp_f32_e32 v2, v2
	s_nop 0
	v_mul_f32_e32 v2, v111, v2
	v_cvt_pk_bf16_f32 v2, v2, s0
	v_alignbit_b32 v115, v2, v108, 16
	v_lshl_add_u64 v[108:109], s[26:27], 0, v[122:123]
	v_lshl_add_u64 v[108:109], v[108:109], 0, v[0:1]
	global_store_dwordx4 v[108:109], v[112:115], off
	s_nop 1
	s_waitcnt vmcnt(12)
; __device__ __forceinline__ float ex2(float x) { return __builtin_amdgcn_exp2f(x); }
;     __device__ __forceinline__ void operator()(const f32x4 (&acc)[2][2][4][2], const pg8::Unit& u, int wr, int wc, int fr, int fq) const {
;         const int row0 = u.pm * 256 + wr * 64 + fr, col0 = u.pn * 256 + wc * 32 + 8 * fq;
; #pragma unroll
;         for (int ai = 0; ai < 2; ++ai)
; #pragma unroll
;             for (int m = 0; m < 4; ++m) { const size_t row = (size_t)(row0 + ai * 128 + m * 16);
; #pragma unroll
;                 for (int bj = 0; bj < 2; ++bj) { const h8 gb = *(const h8*)(P + row * NIN + col0 + C_MS + bj * 128);
;                     h8 o;
; #pragma unroll
;                     for (int n = 0; n < 2; ++n)
; #pragma unroll
;                         for (int i = 0; i < 4; ++i) o[4 * n + i] = op16(acc[ai][bj][m][n][i] * __builtin_amdgcn_rcpf(1.f + ex2((float)gb[4 * n + i] * -1.44269504f)), TAIL_BF16);
;                     *(h8*)(O + row * DM + col0 + bj * 128) = o; } }
;     }
	v_mov_b32_e32 v110, v204
	v_mov_b32_e32 v111, v205
	v_mov_b32_e32 v112, v206
	v_mov_b32_e32 v113, v207
	s_nop 0
	v_cvt_f32_f16_e32 v2, v110
	v_mul_f32_e32 v2, 0xbfb8aa3b, v2
	v_exp_f32_e32 v2, v2
	s_nop 0
	v_add_f32_e32 v2, 1.0, v2
	v_rcp_f32_e32 v2, v2
	s_nop 0
	v_mul_f32_e32 v2, v104, v2
	v_cvt_f32_f16_sdwa v104, v110 dst_sel:DWORD dst_unused:UNUSED_PAD src0_sel:WORD_1
	v_cvt_pk_bf16_f32 v2, v2, s0
	v_mul_f32_e32 v104, 0xbfb8aa3b, v104
	v_exp_f32_e32 v104, v104
	s_nop 0
	v_add_f32_e32 v104, 1.0, v104
	v_rcp_f32_e32 v114, v104
	v_cvt_f32_f16_e32 v104, v111
	v_mul_f32_e32 v104, 0xbfb8aa3b, v104
	v_exp_f32_e32 v104, v104
	s_nop 0
	v_add_f32_e32 v104, 1.0, v104
	v_rcp_f32_e32 v115, v104
	v_mov_b32_e32 v104, v105
	v_mov_b32_e32 v105, v106
	v_pk_mov_b32 v[106:107], v[106:107], v[100:101] op_sel:[1,0]
	v_pk_mul_f32 v[104:105], v[104:105], v[114:115]
	v_cvt_f32_f16_sdwa v100, v112 dst_sel:DWORD dst_unused:UNUSED_PAD src0_sel:WORD_1
	v_cvt_pk_bf16_f32 v105, v104, v105
	v_perm_b32 v104, v105, v2, s45
	v_cvt_f32_f16_sdwa v2, v111 dst_sel:DWORD dst_unused:UNUSED_PAD src0_sel:WORD_1
	v_mul_f32_e32 v100, 0xbfb8aa3b, v100
	v_exp_f32_e32 v100, v100
	v_mul_f32_e32 v2, 0xbfb8aa3b, v2
	v_exp_f32_e32 v2, v2
	v_add_f32_e32 v100, 1.0, v100
	v_add_f32_e32 v2, 1.0, v2
	v_rcp_f32_e32 v110, v2
	v_cvt_f32_f16_e32 v2, v112
	v_mul_f32_e32 v2, 0xbfb8aa3b, v2
	v_exp_f32_e32 v2, v2
	s_nop 0
	v_add_f32_e32 v2, 1.0, v2
	v_rcp_f32_e32 v111, v2
	s_nop 0
	v_pk_mul_f32 v[106:107], v[106:107], v[110:111]
	s_nop 0
	v_cvt_pk_bf16_f32 v2, v106, v107
	v_rcp_f32_e32 v106, v100
	v_cvt_f32_f16_e32 v100, v113
	v_alignbit_b32 v105, v2, v105, 16
	v_mul_f32_e32 v100, 0xbfb8aa3b, v100
	v_exp_f32_e32 v100, v100
	s_nop 0
	v_add_f32_e32 v100, 1.0, v100
	v_rcp_f32_e32 v107, v100
	v_mov_b32_e32 v100, v101
	v_mov_b32_e32 v101, v102
	v_pk_mul_f32 v[100:101], v[100:101], v[106:107]
	s_nop 0
	v_cvt_pk_bf16_f32 v100, v100, v101
	v_alignbit_b32 v106, v100, v2, 16
	v_cvt_f32_f16_sdwa v2, v113 dst_sel:DWORD dst_unused:UNUSED_PAD src0_sel:WORD_1
	v_mul_f32_e32 v2, 0xbfb8aa3b, v2
	v_exp_f32_e32 v2, v2
	s_nop 0
	v_add_f32_e32 v2, 1.0, v2
	v_rcp_f32_e32 v2, v2
	s_nop 0
	v_mul_f32_e32 v2, v103, v2
	v_cvt_pk_bf16_f32 v2, v2, s0
	v_alignbit_b32 v107, v2, v100, 16
	v_or_b32_e32 v100, 32, v166
	v_ashrrev_i32_e32 v101, 31, v100
	global_store_dwordx4 v[108:109], v[104:107], off offset:256
	s_nop 1
	v_lshlrev_b64 v[106:107], 12, v[100:101]
	v_mad_i64_i32 v[100:101], s[10:11], v100, s35, v[132:133]
	v_lshl_add_u64 v[100:101], v[100:101], 0, v[0:1]
	v_add_co_u32_e32 v100, vcc, s1, v100
	s_nop 1
	v_addc_co_u32_e32 v101, vcc, 0, v101, vcc
	s_nop 1
	s_waitcnt vmcnt(11)
	v_mov_b32_e32 v102, v208
	v_mov_b32_e32 v103, v209
	v_mov_b32_e32 v104, v210
	v_mov_b32_e32 v105, v211
	s_nop 0
	v_cvt_f32_f16_e32 v2, v102
	v_mul_f32_e32 v2, 0xbfb8aa3b, v2
	v_exp_f32_e32 v2, v2
	s_nop 0
	v_add_f32_e32 v2, 1.0, v2
	v_rcp_f32_e32 v2, v2
	s_nop 0
	v_mul_f32_e32 v2, v96, v2
	v_cvt_f32_f16_sdwa v96, v102 dst_sel:DWORD dst_unused:UNUSED_PAD src0_sel:WORD_1
	v_cvt_pk_bf16_f32 v2, v2, s0
	v_mul_f32_e32 v96, 0xbfb8aa3b, v96
	v_exp_f32_e32 v96, v96
	s_nop 0
	v_add_f32_e32 v96, 1.0, v96
	v_rcp_f32_e32 v108, v96
	v_cvt_f32_f16_e32 v96, v103
	v_mul_f32_e32 v96, 0xbfb8aa3b, v96
	v_exp_f32_e32 v96, v96
	s_nop 0
	v_add_f32_e32 v96, 1.0, v96
	v_rcp_f32_e32 v109, v96
	v_mov_b32_e32 v96, v97
	v_mov_b32_e32 v97, v98
	v_pk_mov_b32 v[98:99], v[98:99], v[92:93] op_sel:[1,0]
	v_pk_mul_f32 v[96:97], v[96:97], v[108:109]
	v_cvt_f32_f16_sdwa v92, v104 dst_sel:DWORD dst_unused:UNUSED_PAD src0_sel:WORD_1
	v_cvt_pk_bf16_f32 v97, v96, v97
	v_perm_b32 v96, v97, v2, s45
	v_cvt_f32_f16_sdwa v2, v103 dst_sel:DWORD dst_unused:UNUSED_PAD src0_sel:WORD_1
	v_mul_f32_e32 v92, 0xbfb8aa3b, v92
	v_exp_f32_e32 v92, v92
	v_mul_f32_e32 v2, 0xbfb8aa3b, v2
	v_exp_f32_e32 v2, v2
	v_add_f32_e32 v92, 1.0, v92
	v_add_f32_e32 v2, 1.0, v2
	v_rcp_f32_e32 v102, v2
	v_cvt_f32_f16_e32 v2, v104
	v_mul_f32_e32 v2, 0xbfb8aa3b, v2
	v_exp_f32_e32 v2, v2
	s_nop 0
	v_add_f32_e32 v2, 1.0, v2
	v_rcp_f32_e32 v103, v2
	s_nop 0
	v_pk_mul_f32 v[98:99], v[98:99], v[102:103]
	s_nop 0
	v_cvt_pk_bf16_f32 v2, v98, v99
	v_rcp_f32_e32 v98, v92
	v_cvt_f32_f16_e32 v92, v105
	v_alignbit_b32 v97, v2, v97, 16
	v_mul_f32_e32 v92, 0xbfb8aa3b, v92
	v_exp_f32_e32 v92, v92
	s_nop 0
	v_add_f32_e32 v92, 1.0, v92
	v_rcp_f32_e32 v99, v92
	v_mov_b32_e32 v92, v93
	v_mov_b32_e32 v93, v94
	v_pk_mul_f32 v[92:93], v[92:93], v[98:99]
	s_nop 0
	v_cvt_pk_bf16_f32 v92, v92, v93
	v_alignbit_b32 v98, v92, v2, 16
	v_cvt_f32_f16_sdwa v2, v105 dst_sel:DWORD dst_unused:UNUSED_PAD src0_sel:WORD_1
	v_mul_f32_e32 v2, 0xbfb8aa3b, v2
	v_exp_f32_e32 v2, v2
	s_nop 0
	v_add_f32_e32 v2, 1.0, v2
	v_rcp_f32_e32 v2, v2
	s_nop 0
	v_mul_f32_e32 v2, v95, v2
	v_cvt_pk_bf16_f32 v2, v2, s0
	v_alignbit_b32 v99, v2, v92, 16
	v_lshl_add_u64 v[92:93], s[26:27], 0, v[106:107]
	v_lshl_add_u64 v[92:93], v[92:93], 0, v[0:1]
	global_store_dwordx4 v[92:93], v[96:99], off
	s_nop 1
	s_waitcnt vmcnt(10)
; __device__ __forceinline__ float ex2(float x) { return __builtin_amdgcn_exp2f(x); }
;     __device__ __forceinline__ void operator()(const f32x4 (&acc)[2][2][4][2], const pg8::Unit& u, int wr, int wc, int fr, int fq) const {
;         const int row0 = u.pm * 256 + wr * 64 + fr, col0 = u.pn * 256 + wc * 32 + 8 * fq;
; #pragma unroll
;         for (int ai = 0; ai < 2; ++ai)
; #pragma unroll
;             for (int m = 0; m < 4; ++m) { const size_t row = (size_t)(row0 + ai * 128 + m * 16);
; #pragma unroll
;                 for (int bj = 0; bj < 2; ++bj) { const h8 gb = *(const h8*)(P + row * NIN + col0 + C_MS + bj * 128);
;                     h8 o;
; #pragma unroll
;                     for (int n = 0; n < 2; ++n)
; #pragma unroll
;                         for (int i = 0; i < 4; ++i) o[4 * n + i] = op16(acc[ai][bj][m][n][i] * __builtin_amdgcn_rcpf(1.f + ex2((float)gb[4 * n + i] * -1.44269504f)), TAIL_BF16);
;                     *(h8*)(O + row * DM + col0 + bj * 128) = o; } }
;     }
	v_mov_b32_e32 v94, v212
	v_mov_b32_e32 v95, v213
	v_mov_b32_e32 v96, v214
	v_mov_b32_e32 v97, v215
	s_nop 0
	v_cvt_f32_f16_e32 v2, v94
	v_mul_f32_e32 v2, 0xbfb8aa3b, v2
	v_exp_f32_e32 v2, v2
	s_nop 0
	v_add_f32_e32 v2, 1.0, v2
	v_rcp_f32_e32 v2, v2
	s_nop 0
	v_mul_f32_e32 v2, v88, v2
	v_cvt_f32_f16_sdwa v88, v94 dst_sel:DWORD dst_unused:UNUSED_PAD src0_sel:WORD_1
	v_cvt_pk_bf16_f32 v2, v2, s0
	v_mul_f32_e32 v88, 0xbfb8aa3b, v88
	v_exp_f32_e32 v88, v88
	s_nop 0
	v_add_f32_e32 v88, 1.0, v88
	v_rcp_f32_e32 v98, v88
	v_cvt_f32_f16_e32 v88, v95
	v_mul_f32_e32 v88, 0xbfb8aa3b, v88
	v_exp_f32_e32 v88, v88
	s_nop 0
	v_add_f32_e32 v88, 1.0, v88
	v_rcp_f32_e32 v99, v88
	v_mov_b32_e32 v88, v89
	v_mov_b32_e32 v89, v90
	v_pk_mov_b32 v[90:91], v[90:91], v[84:85] op_sel:[1,0]
	v_pk_mul_f32 v[88:89], v[88:89], v[98:99]
	v_cvt_f32_f16_sdwa v84, v96 dst_sel:DWORD dst_unused:UNUSED_PAD src0_sel:WORD_1
	v_cvt_pk_bf16_f32 v89, v88, v89
	v_perm_b32 v88, v89, v2, s45
	v_cvt_f32_f16_sdwa v2, v95 dst_sel:DWORD dst_unused:UNUSED_PAD src0_sel:WORD_1
	v_mul_f32_e32 v84, 0xbfb8aa3b, v84
	v_exp_f32_e32 v84, v84
	v_mul_f32_e32 v2, 0xbfb8aa3b, v2
	v_exp_f32_e32 v2, v2
	v_add_f32_e32 v84, 1.0, v84
	v_add_f32_e32 v2, 1.0, v2
	v_rcp_f32_e32 v94, v2
	v_cvt_f32_f16_e32 v2, v96
	v_mul_f32_e32 v2, 0xbfb8aa3b, v2
	v_exp_f32_e32 v2, v2
	s_nop 0
	v_add_f32_e32 v2, 1.0, v2
	v_rcp_f32_e32 v95, v2
	s_nop 0
	v_pk_mul_f32 v[90:91], v[90:91], v[94:95]
	s_nop 0
	v_cvt_pk_bf16_f32 v2, v90, v91
	v_rcp_f32_e32 v90, v84
	v_cvt_f32_f16_e32 v84, v97
	v_alignbit_b32 v89, v2, v89, 16
	v_mul_f32_e32 v84, 0xbfb8aa3b, v84
	v_exp_f32_e32 v84, v84
	s_nop 0
	v_add_f32_e32 v84, 1.0, v84
	v_rcp_f32_e32 v91, v84
	v_mov_b32_e32 v84, v85
	v_mov_b32_e32 v85, v86
	v_pk_mul_f32 v[84:85], v[84:85], v[90:91]
	s_nop 0
	v_cvt_pk_bf16_f32 v84, v84, v85
	v_alignbit_b32 v90, v84, v2, 16
	v_cvt_f32_f16_sdwa v2, v97 dst_sel:DWORD dst_unused:UNUSED_PAD src0_sel:WORD_1
	v_mul_f32_e32 v2, 0xbfb8aa3b, v2
	v_exp_f32_e32 v2, v2
	s_nop 0
	v_add_f32_e32 v2, 1.0, v2
	v_rcp_f32_e32 v2, v2
	s_nop 0
	v_mul_f32_e32 v2, v87, v2
	v_cvt_pk_bf16_f32 v2, v2, s0
	v_alignbit_b32 v91, v2, v84, 16
	v_or_b32_e32 v84, 48, v166
	v_ashrrev_i32_e32 v85, 31, v84
	global_store_dwordx4 v[92:93], v[88:91], off offset:256
	s_nop 1
	v_lshlrev_b64 v[90:91], 12, v[84:85]
	v_mad_i64_i32 v[84:85], s[10:11], v84, s35, v[132:133]
	v_lshl_add_u64 v[84:85], v[84:85], 0, v[0:1]
	v_add_co_u32_e32 v84, vcc, s1, v84
	s_nop 1
	v_addc_co_u32_e32 v85, vcc, 0, v85, vcc
	s_nop 1
	s_waitcnt vmcnt(9)
	v_mov_b32_e32 v86, v216
	v_mov_b32_e32 v87, v217
	v_mov_b32_e32 v88, v218
	v_mov_b32_e32 v89, v219
	s_nop 0
	v_cvt_f32_f16_e32 v2, v86
	v_mul_f32_e32 v2, 0xbfb8aa3b, v2
	v_exp_f32_e32 v2, v2
	s_nop 0
	v_add_f32_e32 v2, 1.0, v2
	v_rcp_f32_e32 v2, v2
	s_nop 0
	v_mul_f32_e32 v2, v80, v2
	v_cvt_f32_f16_sdwa v80, v86 dst_sel:DWORD dst_unused:UNUSED_PAD src0_sel:WORD_1
	v_cvt_pk_bf16_f32 v2, v2, s0
	v_mul_f32_e32 v80, 0xbfb8aa3b, v80
	v_exp_f32_e32 v80, v80
	s_nop 0
	v_add_f32_e32 v80, 1.0, v80
	v_rcp_f32_e32 v92, v80
	v_cvt_f32_f16_e32 v80, v87
	v_mul_f32_e32 v80, 0xbfb8aa3b, v80
	v_exp_f32_e32 v80, v80
	s_nop 0
	v_add_f32_e32 v80, 1.0, v80
	v_rcp_f32_e32 v93, v80
	v_mov_b32_e32 v80, v81
	v_mov_b32_e32 v81, v82
	v_pk_mov_b32 v[82:83], v[82:83], v[76:77] op_sel:[1,0]
	v_pk_mul_f32 v[80:81], v[80:81], v[92:93]
	v_cvt_f32_f16_sdwa v76, v88 dst_sel:DWORD dst_unused:UNUSED_PAD src0_sel:WORD_1
	v_cvt_pk_bf16_f32 v81, v80, v81
	v_perm_b32 v80, v81, v2, s45
	v_cvt_f32_f16_sdwa v2, v87 dst_sel:DWORD dst_unused:UNUSED_PAD src0_sel:WORD_1
	v_mul_f32_e32 v76, 0xbfb8aa3b, v76
	v_exp_f32_e32 v76, v76
	v_mul_f32_e32 v2, 0xbfb8aa3b, v2
	v_exp_f32_e32 v2, v2
	v_add_f32_e32 v76, 1.0, v76
	v_add_f32_e32 v2, 1.0, v2
	v_rcp_f32_e32 v86, v2
	v_cvt_f32_f16_e32 v2, v88
	v_mul_f32_e32 v2, 0xbfb8aa3b, v2
	v_exp_f32_e32 v2, v2
	s_nop 0
	v_add_f32_e32 v2, 1.0, v2
	v_rcp_f32_e32 v87, v2
	s_nop 0
	v_pk_mul_f32 v[82:83], v[82:83], v[86:87]
	s_nop 0
	v_cvt_pk_bf16_f32 v2, v82, v83
	v_rcp_f32_e32 v82, v76
	v_cvt_f32_f16_e32 v76, v89
	v_alignbit_b32 v81, v2, v81, 16
	v_mul_f32_e32 v76, 0xbfb8aa3b, v76
	v_exp_f32_e32 v76, v76
	s_nop 0
	v_add_f32_e32 v76, 1.0, v76
	v_rcp_f32_e32 v83, v76
	v_mov_b32_e32 v76, v77
	v_mov_b32_e32 v77, v78
	v_pk_mul_f32 v[76:77], v[76:77], v[82:83]
	s_nop 0
	v_cvt_pk_bf16_f32 v76, v76, v77
	v_alignbit_b32 v82, v76, v2, 16
	v_cvt_f32_f16_sdwa v2, v89 dst_sel:DWORD dst_unused:UNUSED_PAD src0_sel:WORD_1
	v_mul_f32_e32 v2, 0xbfb8aa3b, v2
	v_exp_f32_e32 v2, v2
	s_nop 0
	v_add_f32_e32 v2, 1.0, v2
	v_rcp_f32_e32 v2, v2
	s_nop 0
	v_mul_f32_e32 v2, v79, v2
	v_cvt_pk_bf16_f32 v2, v2, s0
	v_alignbit_b32 v83, v2, v76, 16
	v_lshl_add_u64 v[76:77], s[26:27], 0, v[90:91]
	v_lshl_add_u64 v[76:77], v[76:77], 0, v[0:1]
	global_store_dwordx4 v[76:77], v[80:83], off
	s_nop 1
	s_waitcnt vmcnt(8)
; __device__ __forceinline__ float ex2(float x) { return __builtin_amdgcn_exp2f(x); }
;     __device__ __forceinline__ void operator()(const f32x4 (&acc)[2][2][4][2], const pg8::Unit& u, int wr, int wc, int fr, int fq) const {
;         const int row0 = u.pm * 256 + wr * 64 + fr, col0 = u.pn * 256 + wc * 32 + 8 * fq;
; #pragma unroll
;         for (int ai = 0; ai < 2; ++ai)
; #pragma unroll
;             for (int m = 0; m < 4; ++m) { const size_t row = (size_t)(row0 + ai * 128 + m * 16);
; #pragma unroll
;                 for (int bj = 0; bj < 2; ++bj) { const h8 gb = *(const h8*)(P + row * NIN + col0 + C_MS + bj * 128);
;                     h8 o;
; #pragma unroll
;                     for (int n = 0; n < 2; ++n)
; #pragma unroll
;                         for (int i = 0; i < 4; ++i) o[4 * n + i] = op16(acc[ai][bj][m][n][i] * __builtin_amdgcn_rcpf(1.f + ex2((float)gb[4 * n + i] * -1.44269504f)), TAIL_BF16);
;                     *(h8*)(O + row * DM + col0 + bj * 128) = o; } }
;     }
	v_mov_b32_e32 v78, v220
	v_mov_b32_e32 v79, v221
	v_mov_b32_e32 v80, v222
	v_mov_b32_e32 v81, v223
	s_nop 0
	v_cvt_f32_f16_e32 v2, v78
	v_mul_f32_e32 v2, 0xbfb8aa3b, v2
	v_exp_f32_e32 v2, v2
	s_nop 0
	v_add_f32_e32 v2, 1.0, v2
	v_rcp_f32_e32 v2, v2
	s_nop 0
	v_mul_f32_e32 v2, v72, v2
	v_cvt_f32_f16_sdwa v72, v78 dst_sel:DWORD dst_unused:UNUSED_PAD src0_sel:WORD_1
	v_cvt_pk_bf16_f32 v2, v2, s0
	v_mul_f32_e32 v72, 0xbfb8aa3b, v72
	v_exp_f32_e32 v72, v72
	s_nop 0
	v_add_f32_e32 v72, 1.0, v72
	v_rcp_f32_e32 v82, v72
	v_cvt_f32_f16_e32 v72, v79
	v_mul_f32_e32 v72, 0xbfb8aa3b, v72
	v_exp_f32_e32 v72, v72
	s_nop 0
	v_add_f32_e32 v72, 1.0, v72
	v_rcp_f32_e32 v83, v72
	v_mov_b32_e32 v72, v73
	v_mov_b32_e32 v73, v74
	v_pk_mov_b32 v[74:75], v[74:75], v[68:69] op_sel:[1,0]
	v_pk_mul_f32 v[72:73], v[72:73], v[82:83]
	v_cvt_f32_f16_sdwa v68, v80 dst_sel:DWORD dst_unused:UNUSED_PAD src0_sel:WORD_1
	v_cvt_pk_bf16_f32 v73, v72, v73
	v_perm_b32 v72, v73, v2, s45
	v_cvt_f32_f16_sdwa v2, v79 dst_sel:DWORD dst_unused:UNUSED_PAD src0_sel:WORD_1
	v_mul_f32_e32 v68, 0xbfb8aa3b, v68
	v_exp_f32_e32 v68, v68
	v_mul_f32_e32 v2, 0xbfb8aa3b, v2
	v_exp_f32_e32 v2, v2
	v_add_f32_e32 v68, 1.0, v68
	v_add_f32_e32 v2, 1.0, v2
	v_rcp_f32_e32 v78, v2
	v_cvt_f32_f16_e32 v2, v80
	v_mul_f32_e32 v2, 0xbfb8aa3b, v2
	v_exp_f32_e32 v2, v2
	s_nop 0
	v_add_f32_e32 v2, 1.0, v2
	v_rcp_f32_e32 v79, v2
	s_nop 0
	v_pk_mul_f32 v[74:75], v[74:75], v[78:79]
	s_nop 0
	v_cvt_pk_bf16_f32 v2, v74, v75
	v_rcp_f32_e32 v74, v68
	v_cvt_f32_f16_e32 v68, v81
	v_alignbit_b32 v73, v2, v73, 16
	v_mul_f32_e32 v68, 0xbfb8aa3b, v68
	v_exp_f32_e32 v68, v68
	s_nop 0
	v_add_f32_e32 v68, 1.0, v68
	v_rcp_f32_e32 v75, v68
	v_mov_b32_e32 v68, v69
	v_mov_b32_e32 v69, v70
	v_pk_mul_f32 v[68:69], v[68:69], v[74:75]
	s_nop 0
	v_cvt_pk_bf16_f32 v68, v68, v69
	v_alignbit_b32 v74, v68, v2, 16
	v_cvt_f32_f16_sdwa v2, v81 dst_sel:DWORD dst_unused:UNUSED_PAD src0_sel:WORD_1
	v_mul_f32_e32 v2, 0xbfb8aa3b, v2
	v_exp_f32_e32 v2, v2
	s_nop 0
	v_add_f32_e32 v2, 1.0, v2
	v_rcp_f32_e32 v2, v2
	s_nop 0
	v_mul_f32_e32 v2, v71, v2
	v_cvt_pk_bf16_f32 v2, v2, s0
	v_alignbit_b32 v75, v2, v68, 16
	v_add_u32_e32 v68, 0x80, v166
	v_ashrrev_i32_e32 v69, 31, v68
	global_store_dwordx4 v[76:77], v[72:75], off offset:256
	s_nop 1
	v_lshlrev_b64 v[74:75], 12, v[68:69]
	v_mad_i64_i32 v[68:69], s[10:11], v68, s35, v[132:133]
	v_lshl_add_u64 v[68:69], v[68:69], 0, v[0:1]
	v_add_co_u32_e32 v68, vcc, s1, v68
	s_nop 1
	v_addc_co_u32_e32 v69, vcc, 0, v69, vcc
	s_nop 1
	s_waitcnt vmcnt(7)
	v_mov_b32_e32 v70, v224
	v_mov_b32_e32 v71, v225
	v_mov_b32_e32 v72, v226
	v_mov_b32_e32 v73, v227
	s_nop 0
	v_cvt_f32_f16_e32 v2, v70
	v_mul_f32_e32 v2, 0xbfb8aa3b, v2
	v_exp_f32_e32 v2, v2
	s_nop 0
	v_add_f32_e32 v2, 1.0, v2
	v_rcp_f32_e32 v2, v2
	s_nop 0
	v_mul_f32_e32 v2, v64, v2
	v_cvt_f32_f16_sdwa v64, v70 dst_sel:DWORD dst_unused:UNUSED_PAD src0_sel:WORD_1
	v_cvt_pk_bf16_f32 v2, v2, s0
	v_mul_f32_e32 v64, 0xbfb8aa3b, v64
	v_exp_f32_e32 v64, v64
	s_nop 0
	v_add_f32_e32 v64, 1.0, v64
	v_rcp_f32_e32 v76, v64
	v_cvt_f32_f16_e32 v64, v71
	v_mul_f32_e32 v64, 0xbfb8aa3b, v64
	v_exp_f32_e32 v64, v64
	s_nop 0
	v_add_f32_e32 v64, 1.0, v64
	v_rcp_f32_e32 v77, v64
	v_mov_b32_e32 v64, v65
	v_mov_b32_e32 v65, v66
	v_pk_mov_b32 v[66:67], v[66:67], v[60:61] op_sel:[1,0]
	v_pk_mul_f32 v[64:65], v[64:65], v[76:77]
	v_cvt_f32_f16_sdwa v60, v72 dst_sel:DWORD dst_unused:UNUSED_PAD src0_sel:WORD_1
	v_cvt_pk_bf16_f32 v65, v64, v65
	v_perm_b32 v64, v65, v2, s45
	v_cvt_f32_f16_sdwa v2, v71 dst_sel:DWORD dst_unused:UNUSED_PAD src0_sel:WORD_1
	v_mul_f32_e32 v60, 0xbfb8aa3b, v60
	v_exp_f32_e32 v60, v60
	v_mul_f32_e32 v2, 0xbfb8aa3b, v2
	v_exp_f32_e32 v2, v2
	v_add_f32_e32 v60, 1.0, v60
	v_add_f32_e32 v2, 1.0, v2
	v_rcp_f32_e32 v70, v2
	v_cvt_f32_f16_e32 v2, v72
	v_mul_f32_e32 v2, 0xbfb8aa3b, v2
	v_exp_f32_e32 v2, v2
	s_nop 0
	v_add_f32_e32 v2, 1.0, v2
	v_rcp_f32_e32 v71, v2
	s_nop 0
	v_pk_mul_f32 v[66:67], v[66:67], v[70:71]
	s_nop 0
	v_cvt_pk_bf16_f32 v2, v66, v67
	v_rcp_f32_e32 v66, v60
	v_cvt_f32_f16_e32 v60, v73
	v_alignbit_b32 v65, v2, v65, 16
	v_mul_f32_e32 v60, 0xbfb8aa3b, v60
	v_exp_f32_e32 v60, v60
	s_nop 0
	v_add_f32_e32 v60, 1.0, v60
	v_rcp_f32_e32 v67, v60
	v_mov_b32_e32 v60, v61
	v_mov_b32_e32 v61, v62
	v_pk_mul_f32 v[60:61], v[60:61], v[66:67]
	s_nop 0
	v_cvt_pk_bf16_f32 v60, v60, v61
	v_alignbit_b32 v66, v60, v2, 16
	v_cvt_f32_f16_sdwa v2, v73 dst_sel:DWORD dst_unused:UNUSED_PAD src0_sel:WORD_1
	v_mul_f32_e32 v2, 0xbfb8aa3b, v2
	v_exp_f32_e32 v2, v2
	s_nop 0
	v_add_f32_e32 v2, 1.0, v2
	v_rcp_f32_e32 v2, v2
	s_nop 0
	v_mul_f32_e32 v2, v63, v2
	v_cvt_pk_bf16_f32 v2, v2, s0
	v_alignbit_b32 v67, v2, v60, 16
	v_lshl_add_u64 v[60:61], s[26:27], 0, v[74:75]
	v_lshl_add_u64 v[60:61], v[60:61], 0, v[0:1]
	global_store_dwordx4 v[60:61], v[64:67], off
	s_nop 1
	s_waitcnt vmcnt(6)
; __device__ __forceinline__ float ex2(float x) { return __builtin_amdgcn_exp2f(x); }
;     __device__ __forceinline__ void operator()(const f32x4 (&acc)[2][2][4][2], const pg8::Unit& u, int wr, int wc, int fr, int fq) const {
;         const int row0 = u.pm * 256 + wr * 64 + fr, col0 = u.pn * 256 + wc * 32 + 8 * fq;
; #pragma unroll
;         for (int ai = 0; ai < 2; ++ai)
; #pragma unroll
;             for (int m = 0; m < 4; ++m) { const size_t row = (size_t)(row0 + ai * 128 + m * 16);
; #pragma unroll
;                 for (int bj = 0; bj < 2; ++bj) { const h8 gb = *(const h8*)(P + row * NIN + col0 + C_MS + bj * 128);
;                     h8 o;
; #pragma unroll
;                     for (int n = 0; n < 2; ++n)
; #pragma unroll
;                         for (int i = 0; i < 4; ++i) o[4 * n + i] = op16(acc[ai][bj][m][n][i] * __builtin_amdgcn_rcpf(1.f + ex2((float)gb[4 * n + i] * -1.44269504f)), TAIL_BF16);
;                     *(h8*)(O + row * DM + col0 + bj * 128) = o; } }
;     }
	v_mov_b32_e32 v62, v228
	v_mov_b32_e32 v63, v229
	v_mov_b32_e32 v64, v230
	v_mov_b32_e32 v65, v231
	s_nop 0
	v_cvt_f32_f16_e32 v2, v62
	v_mul_f32_e32 v2, 0xbfb8aa3b, v2
	v_exp_f32_e32 v2, v2
	s_nop 0
	v_add_f32_e32 v2, 1.0, v2
	v_rcp_f32_e32 v2, v2
	s_nop 0
	v_mul_f32_e32 v2, v56, v2
	v_cvt_f32_f16_sdwa v56, v62 dst_sel:DWORD dst_unused:UNUSED_PAD src0_sel:WORD_1
	v_cvt_pk_bf16_f32 v2, v2, s0
	v_mul_f32_e32 v56, 0xbfb8aa3b, v56
	v_exp_f32_e32 v56, v56
	s_nop 0
	v_add_f32_e32 v56, 1.0, v56
	v_rcp_f32_e32 v66, v56
	v_cvt_f32_f16_e32 v56, v63
	v_mul_f32_e32 v56, 0xbfb8aa3b, v56
	v_exp_f32_e32 v56, v56
	s_nop 0
	v_add_f32_e32 v56, 1.0, v56
	v_rcp_f32_e32 v67, v56
	v_mov_b32_e32 v56, v57
	v_mov_b32_e32 v57, v58
	v_pk_mov_b32 v[58:59], v[58:59], v[52:53] op_sel:[1,0]
	v_pk_mul_f32 v[56:57], v[56:57], v[66:67]
	v_cvt_f32_f16_sdwa v52, v64 dst_sel:DWORD dst_unused:UNUSED_PAD src0_sel:WORD_1
	v_cvt_pk_bf16_f32 v57, v56, v57
	v_perm_b32 v56, v57, v2, s45
	v_cvt_f32_f16_sdwa v2, v63 dst_sel:DWORD dst_unused:UNUSED_PAD src0_sel:WORD_1
	v_mul_f32_e32 v52, 0xbfb8aa3b, v52
	v_exp_f32_e32 v52, v52
	v_mul_f32_e32 v2, 0xbfb8aa3b, v2
	v_exp_f32_e32 v2, v2
	v_add_f32_e32 v52, 1.0, v52
	v_add_f32_e32 v2, 1.0, v2
	v_rcp_f32_e32 v62, v2
	v_cvt_f32_f16_e32 v2, v64
	v_mul_f32_e32 v2, 0xbfb8aa3b, v2
	v_exp_f32_e32 v2, v2
	s_nop 0
	v_add_f32_e32 v2, 1.0, v2
	v_rcp_f32_e32 v63, v2
	s_nop 0
	v_pk_mul_f32 v[58:59], v[58:59], v[62:63]
	s_nop 0
	v_cvt_pk_bf16_f32 v2, v58, v59
	v_rcp_f32_e32 v58, v52
	v_cvt_f32_f16_e32 v52, v65
	v_alignbit_b32 v57, v2, v57, 16
	v_mul_f32_e32 v52, 0xbfb8aa3b, v52
	v_exp_f32_e32 v52, v52
	s_nop 0
	v_add_f32_e32 v52, 1.0, v52
	v_rcp_f32_e32 v59, v52
	v_mov_b32_e32 v52, v53
	v_mov_b32_e32 v53, v54
	v_pk_mul_f32 v[52:53], v[52:53], v[58:59]
	s_nop 0
	v_cvt_pk_bf16_f32 v52, v52, v53
	v_alignbit_b32 v58, v52, v2, 16
	v_cvt_f32_f16_sdwa v2, v65 dst_sel:DWORD dst_unused:UNUSED_PAD src0_sel:WORD_1
	v_mul_f32_e32 v2, 0xbfb8aa3b, v2
	v_exp_f32_e32 v2, v2
	s_nop 0
	v_add_f32_e32 v2, 1.0, v2
	v_rcp_f32_e32 v2, v2
	s_nop 0
	v_mul_f32_e32 v2, v55, v2
	v_cvt_pk_bf16_f32 v2, v2, s0
	v_alignbit_b32 v59, v2, v52, 16
	v_add_u32_e32 v52, 0x90, v166
	v_ashrrev_i32_e32 v53, 31, v52
	global_store_dwordx4 v[60:61], v[56:59], off offset:256
	s_nop 1
	v_lshlrev_b64 v[58:59], 12, v[52:53]
	v_mad_i64_i32 v[52:53], s[10:11], v52, s35, v[132:133]
	v_lshl_add_u64 v[52:53], v[52:53], 0, v[0:1]
	v_add_co_u32_e32 v52, vcc, s1, v52
	s_nop 1
	v_addc_co_u32_e32 v53, vcc, 0, v53, vcc
	s_nop 1
	s_waitcnt vmcnt(5)
	v_mov_b32_e32 v54, v232
	v_mov_b32_e32 v55, v233
	v_mov_b32_e32 v56, v234
	v_mov_b32_e32 v57, v235
	s_nop 0
	v_cvt_f32_f16_e32 v2, v54
	v_mul_f32_e32 v2, 0xbfb8aa3b, v2
	v_exp_f32_e32 v2, v2
	s_nop 0
	v_add_f32_e32 v2, 1.0, v2
	v_rcp_f32_e32 v2, v2
	s_nop 0
	v_mul_f32_e32 v2, v48, v2
	v_cvt_f32_f16_sdwa v48, v54 dst_sel:DWORD dst_unused:UNUSED_PAD src0_sel:WORD_1
	v_cvt_pk_bf16_f32 v2, v2, s0
	v_mul_f32_e32 v48, 0xbfb8aa3b, v48
	v_exp_f32_e32 v48, v48
	s_nop 0
	v_add_f32_e32 v48, 1.0, v48
	v_rcp_f32_e32 v60, v48
	v_cvt_f32_f16_e32 v48, v55
	v_mul_f32_e32 v48, 0xbfb8aa3b, v48
	v_exp_f32_e32 v48, v48
	s_nop 0
	v_add_f32_e32 v48, 1.0, v48
	v_rcp_f32_e32 v61, v48
	v_mov_b32_e32 v48, v49
	v_mov_b32_e32 v49, v50
	v_pk_mov_b32 v[50:51], v[50:51], v[44:45] op_sel:[1,0]
	v_pk_mul_f32 v[48:49], v[48:49], v[60:61]
	v_cvt_f32_f16_sdwa v44, v56 dst_sel:DWORD dst_unused:UNUSED_PAD src0_sel:WORD_1
	v_cvt_pk_bf16_f32 v60, v48, v49
	v_perm_b32 v54, v60, v2, s45
	v_cvt_f32_f16_sdwa v2, v55 dst_sel:DWORD dst_unused:UNUSED_PAD src0_sel:WORD_1
	v_mul_f32_e32 v44, 0xbfb8aa3b, v44
	v_exp_f32_e32 v44, v44
	v_mul_f32_e32 v2, 0xbfb8aa3b, v2
	v_exp_f32_e32 v2, v2
	v_add_f32_e32 v44, 1.0, v44
	v_add_f32_e32 v2, 1.0, v2
	v_rcp_f32_e32 v48, v2
	v_cvt_f32_f16_e32 v2, v56
	v_mul_f32_e32 v2, 0xbfb8aa3b, v2
	v_exp_f32_e32 v2, v2
	s_nop 0
	v_add_f32_e32 v2, 1.0, v2
	v_rcp_f32_e32 v49, v2
	s_nop 0
	v_pk_mul_f32 v[48:49], v[50:51], v[48:49]
	s_nop 0
	v_cvt_pk_bf16_f32 v2, v48, v49
	v_rcp_f32_e32 v48, v44
	v_cvt_f32_f16_e32 v44, v57
	v_alignbit_b32 v55, v2, v60, 16
	v_mul_f32_e32 v44, 0xbfb8aa3b, v44
	v_exp_f32_e32 v44, v44
	s_nop 0
	v_add_f32_e32 v44, 1.0, v44
	v_rcp_f32_e32 v49, v44
	v_mov_b32_e32 v44, v45
	v_mov_b32_e32 v45, v46
	v_pk_mul_f32 v[44:45], v[44:45], v[48:49]
	s_nop 0
	v_cvt_pk_bf16_f32 v44, v44, v45
	v_alignbit_b32 v56, v44, v2, 16
	v_cvt_f32_f16_sdwa v2, v57 dst_sel:DWORD dst_unused:UNUSED_PAD src0_sel:WORD_1
	v_mul_f32_e32 v2, 0xbfb8aa3b, v2
	v_exp_f32_e32 v2, v2
	s_nop 0
	v_add_f32_e32 v2, 1.0, v2
	v_rcp_f32_e32 v2, v2
	s_nop 0
	v_mul_f32_e32 v2, v47, v2
	v_cvt_pk_bf16_f32 v2, v2, s0
	v_alignbit_b32 v57, v2, v44, 16
	v_lshl_add_u64 v[44:45], s[26:27], 0, v[58:59]
	v_lshl_add_u64 v[48:49], v[44:45], 0, v[0:1]
	s_nop 1
	s_waitcnt vmcnt(4)
; __device__ __forceinline__ float ex2(float x) { return __builtin_amdgcn_exp2f(x); }
;     __device__ __forceinline__ void operator()(const f32x4 (&acc)[2][2][4][2], const pg8::Unit& u, int wr, int wc, int fr, int fq) const {
;         const int row0 = u.pm * 256 + wr * 64 + fr, col0 = u.pn * 256 + wc * 32 + 8 * fq;
; #pragma unroll
;         for (int ai = 0; ai < 2; ++ai)
; #pragma unroll
;             for (int m = 0; m < 4; ++m) { const size_t row = (size_t)(row0 + ai * 128 + m * 16);
; #pragma unroll
;                 for (int bj = 0; bj < 2; ++bj) { const h8 gb = *(const h8*)(P + row * NIN + col0 + C_MS + bj * 128);
;                     h8 o;
; #pragma unroll
;                     for (int n = 0; n < 2; ++n)
; #pragma unroll
;                         for (int i = 0; i < 4; ++i) o[4 * n + i] = op16(acc[ai][bj][m][n][i] * __builtin_amdgcn_rcpf(1.f + ex2((float)gb[4 * n + i] * -1.44269504f)), TAIL_BF16);
;                     *(h8*)(O + row * DM + col0 + bj * 128) = o; } }
;     }
	v_mov_b32_e32 v44, v236
	v_mov_b32_e32 v45, v237
	v_mov_b32_e32 v46, v238
	v_mov_b32_e32 v47, v239
	s_nop 0
	v_cvt_f32_f16_e32 v2, v44
	global_store_dwordx4 v[48:49], v[54:57], off
	v_mul_f32_e32 v2, 0xbfb8aa3b, v2
	v_exp_f32_e32 v2, v2
	s_nop 0
	v_add_f32_e32 v2, 1.0, v2
	v_rcp_f32_e32 v2, v2
	s_nop 0
	v_mul_f32_e32 v2, v40, v2
	v_cvt_f32_f16_sdwa v40, v44 dst_sel:DWORD dst_unused:UNUSED_PAD src0_sel:WORD_1
	v_cvt_pk_bf16_f32 v2, v2, s0
	v_mul_f32_e32 v40, 0xbfb8aa3b, v40
	v_exp_f32_e32 v40, v40
	s_nop 0
	v_add_f32_e32 v40, 1.0, v40
	v_rcp_f32_e32 v50, v40
	v_cvt_f32_f16_e32 v40, v45
	v_mul_f32_e32 v40, 0xbfb8aa3b, v40
	v_exp_f32_e32 v40, v40
	s_nop 0
	v_add_f32_e32 v40, 1.0, v40
	v_rcp_f32_e32 v51, v40
	v_mov_b32_e32 v40, v41
	v_mov_b32_e32 v41, v42
	v_pk_mov_b32 v[42:43], v[42:43], v[36:37] op_sel:[1,0]
	v_pk_mul_f32 v[40:41], v[40:41], v[50:51]
	v_cvt_f32_f16_sdwa v36, v46 dst_sel:DWORD dst_unused:UNUSED_PAD src0_sel:WORD_1
	v_cvt_pk_bf16_f32 v41, v40, v41
	v_perm_b32 v40, v41, v2, s45
	v_cvt_f32_f16_sdwa v2, v45 dst_sel:DWORD dst_unused:UNUSED_PAD src0_sel:WORD_1
	v_mul_f32_e32 v36, 0xbfb8aa3b, v36
	v_exp_f32_e32 v36, v36
	v_mul_f32_e32 v2, 0xbfb8aa3b, v2
	v_exp_f32_e32 v2, v2
	v_add_f32_e32 v36, 1.0, v36
	v_add_f32_e32 v2, 1.0, v2
	v_rcp_f32_e32 v44, v2
	v_cvt_f32_f16_e32 v2, v46
	v_mul_f32_e32 v2, 0xbfb8aa3b, v2
	v_exp_f32_e32 v2, v2
	s_nop 0
	v_add_f32_e32 v2, 1.0, v2
	v_rcp_f32_e32 v45, v2
	s_nop 0
	v_pk_mul_f32 v[42:43], v[42:43], v[44:45]
	s_nop 0
	v_cvt_pk_bf16_f32 v2, v42, v43
	v_rcp_f32_e32 v42, v36
	v_cvt_f32_f16_e32 v36, v47
	v_alignbit_b32 v41, v2, v41, 16
	v_mul_f32_e32 v36, 0xbfb8aa3b, v36
	v_exp_f32_e32 v36, v36
	s_nop 0
	v_add_f32_e32 v36, 1.0, v36
	v_rcp_f32_e32 v43, v36
	v_mov_b32_e32 v36, v37
	v_mov_b32_e32 v37, v38
	v_pk_mul_f32 v[36:37], v[36:37], v[42:43]
	s_nop 0
	v_cvt_pk_bf16_f32 v36, v36, v37
	v_alignbit_b32 v42, v36, v2, 16
	v_cvt_f32_f16_sdwa v2, v47 dst_sel:DWORD dst_unused:UNUSED_PAD src0_sel:WORD_1
	v_mul_f32_e32 v2, 0xbfb8aa3b, v2
	v_exp_f32_e32 v2, v2
	s_nop 0
	v_add_f32_e32 v2, 1.0, v2
	v_rcp_f32_e32 v2, v2
	s_nop 0
	v_mul_f32_e32 v2, v39, v2
	v_cvt_pk_bf16_f32 v2, v2, s0
	v_alignbit_b32 v43, v2, v36, 16
	v_add_u32_e32 v36, 0xa0, v166
	v_ashrrev_i32_e32 v37, 31, v36
	global_store_dwordx4 v[48:49], v[40:43], off offset:256
	s_nop 1
	v_lshlrev_b64 v[42:43], 12, v[36:37]
	v_mad_i64_i32 v[36:37], s[10:11], v36, s35, v[132:133]
	v_lshl_add_u64 v[36:37], v[36:37], 0, v[0:1]
	v_add_co_u32_e32 v36, vcc, s1, v36
	s_nop 1
	v_addc_co_u32_e32 v37, vcc, 0, v37, vcc
	s_nop 1
	s_waitcnt vmcnt(3)
	v_mov_b32_e32 v38, v240
	v_mov_b32_e32 v39, v241
	v_mov_b32_e32 v40, v242
	v_mov_b32_e32 v41, v243
	s_nop 0
	v_cvt_f32_f16_e32 v2, v38
	v_mul_f32_e32 v2, 0xbfb8aa3b, v2
	v_exp_f32_e32 v2, v2
	s_nop 0
	v_add_f32_e32 v2, 1.0, v2
	v_rcp_f32_e32 v2, v2
	s_nop 0
	v_mul_f32_e32 v2, v32, v2
	v_cvt_f32_f16_sdwa v32, v38 dst_sel:DWORD dst_unused:UNUSED_PAD src0_sel:WORD_1
	v_cvt_pk_bf16_f32 v2, v2, s0
	v_mul_f32_e32 v32, 0xbfb8aa3b, v32
	v_exp_f32_e32 v32, v32
	s_nop 0
	v_add_f32_e32 v32, 1.0, v32
	v_rcp_f32_e32 v44, v32
	v_cvt_f32_f16_e32 v32, v39
	v_mul_f32_e32 v32, 0xbfb8aa3b, v32
	v_exp_f32_e32 v32, v32
	s_nop 0
	v_add_f32_e32 v32, 1.0, v32
	v_rcp_f32_e32 v45, v32
	v_mov_b32_e32 v32, v33
	v_mov_b32_e32 v33, v34
	v_pk_mov_b32 v[34:35], v[34:35], v[28:29] op_sel:[1,0]
	v_pk_mul_f32 v[32:33], v[32:33], v[44:45]
	v_cvt_f32_f16_sdwa v28, v40 dst_sel:DWORD dst_unused:UNUSED_PAD src0_sel:WORD_1
	v_cvt_pk_bf16_f32 v44, v32, v33
	v_perm_b32 v38, v44, v2, s45
	v_cvt_f32_f16_sdwa v2, v39 dst_sel:DWORD dst_unused:UNUSED_PAD src0_sel:WORD_1
	v_mul_f32_e32 v28, 0xbfb8aa3b, v28
	v_exp_f32_e32 v28, v28
	v_mul_f32_e32 v2, 0xbfb8aa3b, v2
	v_exp_f32_e32 v2, v2
	v_add_f32_e32 v28, 1.0, v28
	v_add_f32_e32 v2, 1.0, v2
	v_rcp_f32_e32 v32, v2
	v_cvt_f32_f16_e32 v2, v40
	v_mul_f32_e32 v2, 0xbfb8aa3b, v2
	v_exp_f32_e32 v2, v2
	s_nop 0
	v_add_f32_e32 v2, 1.0, v2
	v_rcp_f32_e32 v33, v2
	s_nop 0
	v_pk_mul_f32 v[32:33], v[34:35], v[32:33]
	s_nop 0
	v_cvt_pk_bf16_f32 v2, v32, v33
	v_rcp_f32_e32 v32, v28
	v_cvt_f32_f16_e32 v28, v41
	v_alignbit_b32 v39, v2, v44, 16
	v_mul_f32_e32 v28, 0xbfb8aa3b, v28
	v_exp_f32_e32 v28, v28
	s_nop 0
	v_add_f32_e32 v28, 1.0, v28
	v_rcp_f32_e32 v33, v28
	v_mov_b32_e32 v28, v29
	v_mov_b32_e32 v29, v30
	v_pk_mul_f32 v[28:29], v[28:29], v[32:33]
	s_nop 0
	v_cvt_pk_bf16_f32 v28, v28, v29
	v_alignbit_b32 v40, v28, v2, 16
	v_cvt_f32_f16_sdwa v2, v41 dst_sel:DWORD dst_unused:UNUSED_PAD src0_sel:WORD_1
	v_mul_f32_e32 v2, 0xbfb8aa3b, v2
	v_exp_f32_e32 v2, v2
	s_nop 0
	v_add_f32_e32 v2, 1.0, v2
	v_rcp_f32_e32 v2, v2
	s_nop 0
	v_mul_f32_e32 v2, v31, v2
	v_cvt_pk_bf16_f32 v2, v2, s0
	v_alignbit_b32 v41, v2, v28, 16
	v_lshl_add_u64 v[28:29], s[26:27], 0, v[42:43]
	v_lshl_add_u64 v[32:33], v[28:29], 0, v[0:1]
	s_nop 1
	s_waitcnt vmcnt(2)
; __device__ __forceinline__ float ex2(float x) { return __builtin_amdgcn_exp2f(x); }
;     __device__ __forceinline__ void operator()(const f32x4 (&acc)[2][2][4][2], const pg8::Unit& u, int wr, int wc, int fr, int fq) const {
;         const int row0 = u.pm * 256 + wr * 64 + fr, col0 = u.pn * 256 + wc * 32 + 8 * fq;
; #pragma unroll
;         for (int ai = 0; ai < 2; ++ai)
; #pragma unroll
;             for (int m = 0; m < 4; ++m) { const size_t row = (size_t)(row0 + ai * 128 + m * 16);
; #pragma unroll
;                 for (int bj = 0; bj < 2; ++bj) { const h8 gb = *(const h8*)(P + row * NIN + col0 + C_MS + bj * 128);
;                     h8 o;
; #pragma unroll
;                     for (int n = 0; n < 2; ++n)
; #pragma unroll
;                         for (int i = 0; i < 4; ++i) o[4 * n + i] = op16(acc[ai][bj][m][n][i] * __builtin_amdgcn_rcpf(1.f + ex2((float)gb[4 * n + i] * -1.44269504f)), TAIL_BF16);
;                     *(h8*)(O + row * DM + col0 + bj * 128) = o; } }
;     }
	v_mov_b32_e32 v28, v244
	v_mov_b32_e32 v29, v245
	v_mov_b32_e32 v30, v246
	v_mov_b32_e32 v31, v247
	s_nop 0
	v_cvt_f32_f16_e32 v2, v28
	global_store_dwordx4 v[32:33], v[38:41], off
	v_mul_f32_e32 v2, 0xbfb8aa3b, v2
	v_exp_f32_e32 v2, v2
	s_nop 0
	v_add_f32_e32 v2, 1.0, v2
	v_rcp_f32_e32 v2, v2
	s_nop 0
	v_mul_f32_e32 v2, v24, v2
	v_cvt_f32_f16_sdwa v24, v28 dst_sel:DWORD dst_unused:UNUSED_PAD src0_sel:WORD_1
	v_cvt_pk_bf16_f32 v2, v2, s0
	v_mul_f32_e32 v24, 0xbfb8aa3b, v24
	v_exp_f32_e32 v24, v24
	s_nop 0
	v_add_f32_e32 v24, 1.0, v24
	v_rcp_f32_e32 v34, v24
	v_cvt_f32_f16_e32 v24, v29
	v_mul_f32_e32 v24, 0xbfb8aa3b, v24
	v_exp_f32_e32 v24, v24
	s_nop 0
	v_add_f32_e32 v24, 1.0, v24
	v_rcp_f32_e32 v35, v24
	v_mov_b32_e32 v24, v25
	v_mov_b32_e32 v25, v26
	v_pk_mov_b32 v[26:27], v[26:27], v[20:21] op_sel:[1,0]
	v_pk_mul_f32 v[24:25], v[24:25], v[34:35]
	v_cvt_f32_f16_sdwa v20, v30 dst_sel:DWORD dst_unused:UNUSED_PAD src0_sel:WORD_1
	v_cvt_pk_bf16_f32 v25, v24, v25
	v_perm_b32 v24, v25, v2, s45
	v_cvt_f32_f16_sdwa v2, v29 dst_sel:DWORD dst_unused:UNUSED_PAD src0_sel:WORD_1
	v_mul_f32_e32 v20, 0xbfb8aa3b, v20
	v_exp_f32_e32 v20, v20
	v_mul_f32_e32 v2, 0xbfb8aa3b, v2
	v_exp_f32_e32 v2, v2
	v_add_f32_e32 v20, 1.0, v20
	v_add_f32_e32 v2, 1.0, v2
	v_rcp_f32_e32 v28, v2
	v_cvt_f32_f16_e32 v2, v30
	v_mul_f32_e32 v2, 0xbfb8aa3b, v2
	v_exp_f32_e32 v2, v2
	s_nop 0
	v_add_f32_e32 v2, 1.0, v2
	v_rcp_f32_e32 v29, v2
	s_nop 0
	v_pk_mul_f32 v[26:27], v[26:27], v[28:29]
	s_nop 0
	v_cvt_pk_bf16_f32 v2, v26, v27
	v_rcp_f32_e32 v26, v20
	v_cvt_f32_f16_e32 v20, v31
	v_alignbit_b32 v25, v2, v25, 16
	v_mul_f32_e32 v20, 0xbfb8aa3b, v20
	v_exp_f32_e32 v20, v20
	s_nop 0
	v_add_f32_e32 v20, 1.0, v20
	v_rcp_f32_e32 v27, v20
	v_mov_b32_e32 v20, v21
	v_mov_b32_e32 v21, v22
	v_pk_mul_f32 v[20:21], v[20:21], v[26:27]
	s_nop 0
	v_cvt_pk_bf16_f32 v20, v20, v21
	v_alignbit_b32 v26, v20, v2, 16
	v_cvt_f32_f16_sdwa v2, v31 dst_sel:DWORD dst_unused:UNUSED_PAD src0_sel:WORD_1
	v_mul_f32_e32 v2, 0xbfb8aa3b, v2
	v_exp_f32_e32 v2, v2
	s_nop 0
	v_add_f32_e32 v2, 1.0, v2
	v_rcp_f32_e32 v2, v2
	s_nop 0
	v_mul_f32_e32 v2, v23, v2
	v_cvt_pk_bf16_f32 v2, v2, s0
	v_alignbit_b32 v27, v2, v20, 16
	v_add_u32_e32 v20, 0xb0, v166
	v_ashrrev_i32_e32 v21, 31, v20
	global_store_dwordx4 v[32:33], v[24:27], off offset:256
	s_nop 1
	v_lshlrev_b64 v[26:27], 12, v[20:21]
	v_mad_i64_i32 v[20:21], s[10:11], v20, s35, v[132:133]
	v_lshl_add_u64 v[20:21], v[20:21], 0, v[0:1]
	v_add_co_u32_e32 v20, vcc, s1, v20
	s_mov_b64 s[10:11], s[6:7]
	s_nop 0
	v_addc_co_u32_e32 v21, vcc, 0, v21, vcc
	s_nop 1
	s_waitcnt vmcnt(1)
; __device__ __forceinline__ float ex2(float x) { return __builtin_amdgcn_exp2f(x); }
;     __device__ __forceinline__ void operator()(const f32x4 (&acc)[2][2][4][2], const pg8::Unit& u, int wr, int wc, int fr, int fq) const {
;         const int row0 = u.pm * 256 + wr * 64 + fr, col0 = u.pn * 256 + wc * 32 + 8 * fq;
; #pragma unroll
;         for (int ai = 0; ai < 2; ++ai)
; #pragma unroll
;             for (int m = 0; m < 4; ++m) { const size_t row = (size_t)(row0 + ai * 128 + m * 16);
; #pragma unroll
;                 for (int bj = 0; bj < 2; ++bj) { const h8 gb = *(const h8*)(P + row * NIN + col0 + C_MS + bj * 128);
;                     h8 o;
; #pragma unroll
;                     for (int n = 0; n < 2; ++n)
; #pragma unroll
;                         for (int i = 0; i < 4; ++i) o[4 * n + i] = op16(acc[ai][bj][m][n][i] * __builtin_amdgcn_rcpf(1.f + ex2((float)gb[4 * n + i] * -1.44269504f)), TAIL_BF16);
;                     *(h8*)(O + row * DM + col0 + bj * 128) = o; } }
;     }
	v_mov_b32_e32 v22, v172
	v_mov_b32_e32 v23, v173
	v_mov_b32_e32 v24, v174
	v_mov_b32_e32 v25, v175
	s_and_b64 vcc, exec, s[40:41]
	s_nop 0
	v_cvt_f32_f16_e32 v2, v22
	v_mul_f32_e32 v2, 0xbfb8aa3b, v2
	v_exp_f32_e32 v2, v2
	s_nop 0
	v_add_f32_e32 v2, 1.0, v2
	v_rcp_f32_e32 v2, v2
	s_nop 0
	v_mul_f32_e32 v2, v16, v2
	v_cvt_f32_f16_sdwa v16, v22 dst_sel:DWORD dst_unused:UNUSED_PAD src0_sel:WORD_1
	v_cvt_pk_bf16_f32 v2, v2, s0
	v_mul_f32_e32 v16, 0xbfb8aa3b, v16
	v_exp_f32_e32 v16, v16
	s_nop 0
	v_add_f32_e32 v16, 1.0, v16
	v_rcp_f32_e32 v28, v16
	v_cvt_f32_f16_e32 v16, v23
	v_mul_f32_e32 v16, 0xbfb8aa3b, v16
	v_exp_f32_e32 v16, v16
	s_nop 0
	v_add_f32_e32 v16, 1.0, v16
	v_rcp_f32_e32 v29, v16
	v_mov_b32_e32 v16, v17
	v_mov_b32_e32 v17, v18
	v_pk_mov_b32 v[18:19], v[18:19], v[12:13] op_sel:[1,0]
	v_pk_mul_f32 v[16:17], v[16:17], v[28:29]
	v_cvt_f32_f16_sdwa v12, v24 dst_sel:DWORD dst_unused:UNUSED_PAD src0_sel:WORD_1
	v_cvt_pk_bf16_f32 v17, v16, v17
	v_perm_b32 v16, v17, v2, s45
	v_cvt_f32_f16_sdwa v2, v23 dst_sel:DWORD dst_unused:UNUSED_PAD src0_sel:WORD_1
	v_mul_f32_e32 v12, 0xbfb8aa3b, v12
	v_exp_f32_e32 v12, v12
	v_mul_f32_e32 v2, 0xbfb8aa3b, v2
	v_exp_f32_e32 v2, v2
	v_add_f32_e32 v12, 1.0, v12
	v_add_f32_e32 v2, 1.0, v2
	v_rcp_f32_e32 v22, v2
	v_cvt_f32_f16_e32 v2, v24
	v_mul_f32_e32 v2, 0xbfb8aa3b, v2
	v_exp_f32_e32 v2, v2
	s_nop 0
	v_add_f32_e32 v2, 1.0, v2
	v_rcp_f32_e32 v23, v2
	s_nop 0
	v_pk_mul_f32 v[18:19], v[18:19], v[22:23]
	s_nop 0
	v_cvt_pk_bf16_f32 v2, v18, v19
	v_rcp_f32_e32 v18, v12
	v_cvt_f32_f16_e32 v12, v25
	v_alignbit_b32 v17, v2, v17, 16
	v_mul_f32_e32 v12, 0xbfb8aa3b, v12
	v_exp_f32_e32 v12, v12
	s_nop 0
	v_add_f32_e32 v12, 1.0, v12
	v_rcp_f32_e32 v19, v12
	v_mov_b32_e32 v12, v13
	v_mov_b32_e32 v13, v14
	v_pk_mul_f32 v[12:13], v[12:13], v[18:19]
	s_nop 0
	v_cvt_pk_bf16_f32 v12, v12, v13
	v_alignbit_b32 v18, v12, v2, 16
	v_cvt_f32_f16_sdwa v2, v25 dst_sel:DWORD dst_unused:UNUSED_PAD src0_sel:WORD_1
	v_mul_f32_e32 v2, 0xbfb8aa3b, v2
	v_exp_f32_e32 v2, v2
	s_nop 0
	v_add_f32_e32 v2, 1.0, v2
	v_rcp_f32_e32 v2, v2
	s_nop 0
	v_mul_f32_e32 v2, v15, v2
	v_cvt_pk_bf16_f32 v2, v2, s0
	v_alignbit_b32 v19, v2, v12, 16
	v_lshl_add_u64 v[12:13], s[26:27], 0, v[26:27]
	v_lshl_add_u64 v[0:1], v[12:13], 0, v[0:1]
	s_nop 1
	s_waitcnt vmcnt(0)
	v_mov_b32_e32 v12, v176
	v_mov_b32_e32 v13, v177
	v_mov_b32_e32 v14, v178
	v_mov_b32_e32 v15, v179
	s_nop 0
	v_cvt_f32_f16_e32 v2, v12
	global_store_dwordx4 v[0:1], v[16:19], off
	v_mul_f32_e32 v2, 0xbfb8aa3b, v2
	v_exp_f32_e32 v2, v2
	s_nop 0
	v_add_f32_e32 v2, 1.0, v2
	v_rcp_f32_e32 v2, v2
	s_nop 0
	v_mul_f32_e32 v2, v8, v2
	v_cvt_f32_f16_sdwa v8, v12 dst_sel:DWORD dst_unused:UNUSED_PAD src0_sel:WORD_1
	v_cvt_pk_bf16_f32 v2, v2, s0
	v_mul_f32_e32 v8, 0xbfb8aa3b, v8
	v_exp_f32_e32 v8, v8
	s_nop 0
	v_add_f32_e32 v8, 1.0, v8
	v_rcp_f32_e32 v16, v8
	v_cvt_f32_f16_e32 v8, v13
	v_mul_f32_e32 v8, 0xbfb8aa3b, v8
	v_exp_f32_e32 v8, v8
	s_nop 0
	v_add_f32_e32 v8, 1.0, v8
	v_rcp_f32_e32 v17, v8
	v_mov_b32_e32 v8, v9
	v_mov_b32_e32 v9, v10
	v_pk_mov_b32 v[10:11], v[10:11], v[4:5] op_sel:[1,0]
	v_pk_mul_f32 v[8:9], v[8:9], v[16:17]
	v_cvt_f32_f16_sdwa v4, v14 dst_sel:DWORD dst_unused:UNUSED_PAD src0_sel:WORD_1
	v_cvt_pk_bf16_f32 v9, v8, v9
	v_perm_b32 v8, v9, v2, s45
	v_cvt_f32_f16_sdwa v2, v13 dst_sel:DWORD dst_unused:UNUSED_PAD src0_sel:WORD_1
	v_mul_f32_e32 v4, 0xbfb8aa3b, v4
	v_exp_f32_e32 v4, v4
	v_mul_f32_e32 v2, 0xbfb8aa3b, v2
	v_exp_f32_e32 v2, v2
	v_add_f32_e32 v4, 1.0, v4
	v_add_f32_e32 v2, 1.0, v2
	v_rcp_f32_e32 v12, v2
	v_cvt_f32_f16_e32 v2, v14
	v_mul_f32_e32 v2, 0xbfb8aa3b, v2
	v_exp_f32_e32 v2, v2
	s_nop 0
	v_add_f32_e32 v2, 1.0, v2
	v_rcp_f32_e32 v13, v2
	s_nop 0
	v_pk_mul_f32 v[10:11], v[10:11], v[12:13]
	s_nop 0
	v_cvt_pk_bf16_f32 v2, v10, v11
	v_rcp_f32_e32 v10, v4
	v_cvt_f32_f16_e32 v4, v15
	v_alignbit_b32 v9, v2, v9, 16
	v_mul_f32_e32 v4, 0xbfb8aa3b, v4
	v_exp_f32_e32 v4, v4
	s_nop 0
	v_add_f32_e32 v4, 1.0, v4
	v_rcp_f32_e32 v11, v4
	v_mov_b32_e32 v4, v5
	v_mov_b32_e32 v5, v6
	v_pk_mul_f32 v[4:5], v[4:5], v[10:11]
	s_nop 0
	v_cvt_pk_bf16_f32 v4, v4, v5
	v_alignbit_b32 v10, v4, v2, 16
	v_cvt_f32_f16_sdwa v2, v15 dst_sel:DWORD dst_unused:UNUSED_PAD src0_sel:WORD_1
	v_mul_f32_e32 v2, 0xbfb8aa3b, v2
	v_exp_f32_e32 v2, v2
	s_nop 0
	v_add_f32_e32 v2, 1.0, v2
	v_rcp_f32_e32 v2, v2
	s_nop 0
	v_mul_f32_e32 v2, v7, v2
	v_cvt_pk_bf16_f32 v2, v2, s0
	v_alignbit_b32 v11, v2, v4, 16
	global_store_dwordx4 v[0:1], v[8:11], off offset:256
	s_cbranch_vccnz .LBB0_597

; #define PG8_STAGE(bufoff, gbase, voff) do { _Pragma("unroll") for (int _i = 0; _i < 2; ++_i) \
;         __builtin_amdgcn_global_load_lds((const unsigned*)((const char*)(gbase) + (voff)[_i]), (LAS unsigned*)(lds + (bufoff) + ldsw + _i * 8192), 16, 0, 0); } while (0)
; #define PG8_LDA(dst, b, h) do { _Pragma("unroll") for (int m = 0; m < 4; ++m) _Pragma("unroll") for (int k = 0; k < 2; ++k) dst[m][k] = *(const LAS h8*)(lds + PG8_SA(b, h) + aoff + m * 2048 + k * 1024); } while (0)
; #define PG8_LDB(dst, b, h) do { _Pragma("unroll") for (int n = 0; n < 2; ++n) _Pragma("unroll") for (int k = 0; k < 2; ++k) dst[n][k] = *(const LAS h8*)(lds + PG8_SB(b, h) + boff + n * 2048 + k * 1024); } while (0)
; #define PG8_WAIT_V(n) asm volatile("s_waitcnt vmcnt(" #n ")" ::: "memory")
; #define PG8_WAIT_L(n) asm volatile("s_waitcnt lgkmcnt(" #n ")" ::: "memory")
; #define PG8_BAR __builtin_amdgcn_s_barrier()
; #define PG8_SCHED __builtin_amdgcn_sched_barrier(0)
; template <class Epi>
; __device__ __forceinline__ void gemm_phase(LAS unsigned char* lds, const Gemm g, const StaticOrder& S, const Epi& E, const int tid) {
;     ...
;             PG8_LDB(B0, 0, 0); PG8_SCHED; PG8_LDA(At, 0, 0); PG8_STAGE(PG8_SA(1, 1), a1 + hstep, voffA);
;             PG8_WAIT_L(8); PG8_BAR; PG8_WAIT_L(0); PG8_MMA(0, 0, At, B0); PG8_BAR; PG8_SCHED;
;             PG8_LDB(B1, 0, 1); PG8_STAGE(PG8_SB(0, 0), b2, voffB);
;             PG8_BAR; PG8_WAIT_L(0); PG8_MMA(0, 1, At, B1); PG8_BAR;
;             PG8_LDA(At, 0, 1); PG8_STAGE(PG8_SA(0, 0), a2, voffA);
;             PG8_BAR; PG8_WAIT_L(0); PG8_MMA(1, 0, At, B0); PG8_BAR; PG8_SCHED;
;             PG8_STAGE(PG8_SB(0, 1), b2 + hstepB, voffB);
;             PG8_WAIT_V(6); PG8_BAR; PG8_MMA(1, 1, At, B1); PG8_BAR;
.LBB0_660:
	s_add_u32 s14, s12, 0xfff80080
	s_addc_u32 s15, s13, -1
	s_add_i32 s57, 0, 0x10000
	v_add_u32_e32 v64, s57, v190
	ds_read_b128 v[28:31], v64
	ds_read_b128 v[32:35], v64 offset:1024
	ds_read_b128 v[60:63], v64 offset:2048
	ds_read_b128 v[64:67], v64 offset:3072
	s_cmp_eq_u32 s56, 28
	s_cselect_b32 s19, s7, s15
	s_cselect_b32 s18, s52, s14
	s_cselect_b32 s15, s1, s55
	s_cselect_b32 s14, s53, s54
	v_lshl_add_u64 v[174:175], s[12:13], 0, v[166:167]
	s_add_i32 m0, s41, 0xc000
	ds_read_b128 v[170:173], v192
	ds_read_b128 v[194:197], v192 offset:1024
	ds_read_b128 v[198:201], v192 offset:2048
	ds_read_b128 v[202:205], v192 offset:3072
	ds_read_b128 v[206:209], v192 offset:4096
	ds_read_b128 v[210:213], v192 offset:5120
	ds_read_b128 v[214:217], v192 offset:6144
	ds_read_b128 v[218:221], v192 offset:7168
	global_load_lds_dwordx4 v[174:175], off
	v_lshl_add_u64 v[174:175], s[12:13], 0, v[168:169]
	s_add_i32 m0, s41, 0xe000
	s_nop 0
	global_load_lds_dwordx4 v[174:175], off
	s_waitcnt lgkmcnt(8)
	s_barrier
	s_waitcnt lgkmcnt(0)
	s_setprio 1
	s_waitcnt lgkmcnt(0)
	v_mfma_f32_16x16x32_bf16 v[144:147], v[28:31], v[170:173], v[144:147]
	v_mfma_f32_16x16x32_bf16 v[140:143], v[60:63], v[170:173], v[140:143]
	v_mfma_f32_16x16x32_bf16 v[128:131], v[28:31], v[198:201], v[128:131]
	v_mfma_f32_16x16x32_bf16 v[124:127], v[60:63], v[198:201], v[124:127]
	v_mfma_f32_16x16x32_bf16 v[112:115], v[28:31], v[206:209], v[112:115]
	v_mfma_f32_16x16x32_bf16 v[108:111], v[60:63], v[206:209], v[108:111]
	v_mfma_f32_16x16x32_bf16 v[96:99], v[28:31], v[214:217], v[96:99]
	v_mfma_f32_16x16x32_bf16 v[92:95], v[60:63], v[214:217], v[92:95]
	v_mfma_f32_16x16x32_bf16 v[144:147], v[32:35], v[194:197], v[144:147]
	v_mfma_f32_16x16x32_bf16 v[140:143], v[64:67], v[194:197], v[140:143]
	v_mfma_f32_16x16x32_bf16 v[128:131], v[32:35], v[202:205], v[128:131]
	v_mfma_f32_16x16x32_bf16 v[124:127], v[64:67], v[202:205], v[124:127]
	v_mfma_f32_16x16x32_bf16 v[112:115], v[32:35], v[210:213], v[112:115]
	v_mfma_f32_16x16x32_bf16 v[108:111], v[64:67], v[210:213], v[108:111]
	v_mfma_f32_16x16x32_bf16 v[96:99], v[32:35], v[218:221], v[96:99]
	v_mfma_f32_16x16x32_bf16 v[92:95], v[64:67], v[218:221], v[92:95]
	s_setprio 0
	s_barrier
	s_add_i32 s60, 0, 0x14000
	v_add_u32_e32 v174, s60, v190
	s_add_i32 s57, s57, s40
	ds_read_b128 v[222:225], v174
	ds_read_b128 v[226:229], v174 offset:1024
	ds_read_b128 v[230:233], v174 offset:2048
	ds_read_b128 v[234:237], v174 offset:3072
	v_lshl_add_u64 v[174:175], s[14:15], 0, v[2:3]
	s_mov_b32 m0, s57
	v_lshl_add_u64 v[238:239], s[14:15], 0, v[0:1]
	global_load_lds_dwordx4 v[174:175], off
	s_add_i32 m0, s57, 0x2000
	s_nop 0
	global_load_lds_dwordx4 v[238:239], off
	s_barrier
	s_waitcnt lgkmcnt(0)
	s_setprio 1
	s_waitcnt lgkmcnt(0)
	v_mfma_f32_16x16x32_bf16 v[136:139], v[222:225], v[170:173], v[136:139]
	v_mfma_f32_16x16x32_bf16 v[132:135], v[230:233], v[170:173], v[132:135]
	v_mfma_f32_16x16x32_bf16 v[120:123], v[222:225], v[198:201], v[120:123]
	v_mfma_f32_16x16x32_bf16 v[116:119], v[230:233], v[198:201], v[116:119]
	v_mfma_f32_16x16x32_bf16 v[104:107], v[222:225], v[206:209], v[104:107]
	v_mfma_f32_16x16x32_bf16 v[100:103], v[230:233], v[206:209], v[100:103]
	v_mfma_f32_16x16x32_bf16 v[88:91], v[222:225], v[214:217], v[88:91]
	v_mfma_f32_16x16x32_bf16 v[84:87], v[230:233], v[214:217], v[84:87]
	v_mfma_f32_16x16x32_bf16 v[136:139], v[226:229], v[194:197], v[136:139]
	v_mfma_f32_16x16x32_bf16 v[132:135], v[234:237], v[194:197], v[132:135]
	v_mfma_f32_16x16x32_bf16 v[120:123], v[226:229], v[202:205], v[120:123]
	v_mfma_f32_16x16x32_bf16 v[116:119], v[234:237], v[202:205], v[116:119]
	v_mfma_f32_16x16x32_bf16 v[104:107], v[226:229], v[210:213], v[104:107]
	v_mfma_f32_16x16x32_bf16 v[100:103], v[234:237], v[210:213], v[100:103]
	v_mfma_f32_16x16x32_bf16 v[88:91], v[226:229], v[218:221], v[88:91]
	v_mfma_f32_16x16x32_bf16 v[84:87], v[234:237], v[218:221], v[84:87]
	s_setprio 0
	s_mov_b32 m0, s41
	v_lshl_add_u64 v[240:241], s[18:19], 0, v[164:165]
	s_barrier
	ds_read_b128 v[170:173], v192 offset:16384
	ds_read_b128 v[194:197], v192 offset:17408
	ds_read_b128 v[198:201], v192 offset:18432
	ds_read_b128 v[202:205], v192 offset:19456
	ds_read_b128 v[206:209], v192 offset:20480
	ds_read_b128 v[210:213], v192 offset:21504
	ds_read_b128 v[214:217], v192 offset:22528
	ds_read_b128 v[218:221], v192 offset:23552
	global_load_lds_dwordx4 v[240:241], off
	v_lshl_add_u64 v[242:243], s[18:19], 0, v[162:163]
	s_mov_b32 m0, s42
	s_nop 0
	global_load_lds_dwordx4 v[242:243], off
	s_barrier
	s_waitcnt lgkmcnt(0)
	s_setprio 1
	s_waitcnt lgkmcnt(0)
	v_mfma_f32_16x16x32_bf16 v[80:83], v[28:31], v[170:173], v[80:83]
	v_mfma_f32_16x16x32_bf16 v[76:79], v[60:63], v[170:173], v[76:79]
	v_mfma_f32_16x16x32_bf16 v[56:59], v[28:31], v[198:201], v[56:59]
	v_mfma_f32_16x16x32_bf16 v[52:55], v[60:63], v[198:201], v[52:55]
	v_mfma_f32_16x16x32_bf16 v[40:43], v[28:31], v[206:209], v[40:43]
	v_mfma_f32_16x16x32_bf16 v[36:39], v[60:63], v[206:209], v[36:39]
	v_mfma_f32_16x16x32_bf16 v[16:19], v[28:31], v[214:217], v[16:19]
	v_mfma_f32_16x16x32_bf16 v[12:15], v[60:63], v[214:217], v[12:15]
	v_mfma_f32_16x16x32_bf16 v[80:83], v[32:35], v[194:197], v[80:83]
	v_mfma_f32_16x16x32_bf16 v[76:79], v[64:67], v[194:197], v[76:79]
	v_mfma_f32_16x16x32_bf16 v[56:59], v[32:35], v[202:205], v[56:59]
	v_mfma_f32_16x16x32_bf16 v[52:55], v[64:67], v[202:205], v[52:55]
	v_mfma_f32_16x16x32_bf16 v[40:43], v[32:35], v[210:213], v[40:43]
	v_mfma_f32_16x16x32_bf16 v[36:39], v[64:67], v[210:213], v[36:39]
	v_mfma_f32_16x16x32_bf16 v[16:19], v[32:35], v[218:221], v[16:19]
	v_mfma_f32_16x16x32_bf16 v[12:15], v[64:67], v[218:221], v[12:15]
	s_setprio 0
	s_barrier
; #define PG8_STAGE(bufoff, gbase, voff) do { _Pragma("unroll") for (int _i = 0; _i < 2; ++_i) \
;         __builtin_amdgcn_global_load_lds((const unsigned*)((const char*)(gbase) + (voff)[_i]), (LAS unsigned*)(lds + (bufoff) + ldsw + _i * 8192), 16, 0, 0); } while (0)
; #define PG8_LDA(dst, b, h) do { _Pragma("unroll") for (int m = 0; m < 4; ++m) _Pragma("unroll") for (int k = 0; k < 2; ++k) dst[m][k] = *(const LAS h8*)(lds + PG8_SA(b, h) + aoff + m * 2048 + k * 1024); } while (0)
; #define PG8_LDB(dst, b, h) do { _Pragma("unroll") for (int n = 0; n < 2; ++n) _Pragma("unroll") for (int k = 0; k < 2; ++k) dst[n][k] = *(const LAS h8*)(lds + PG8_SB(b, h) + boff + n * 2048 + k * 1024); } while (0)
; #define PG8_WAIT_V(n) asm volatile("s_waitcnt vmcnt(" #n ")" ::: "memory")
; #define PG8_WAIT_L(n) asm volatile("s_waitcnt lgkmcnt(" #n ")" ::: "memory")
; #define PG8_BAR __builtin_amdgcn_s_barrier()
; #define PG8_SCHED __builtin_amdgcn_sched_barrier(0)
; template <class Epi>
; __device__ __forceinline__ void gemm_phase(LAS unsigned char* lds, const Gemm g, const StaticOrder& S, const Epi& E, const int tid) {
;     ...
;             PG8_WAIT_V(6); PG8_BAR; PG8_MMA(1, 1, At, B1); PG8_BAR;
;             PG8_LDB(B0, 1, 0); PG8_SCHED; PG8_LDA(At, 1, 0); PG8_STAGE(PG8_SA(0, 1), a2 + hstep, voffA);
;             PG8_WAIT_L(8); PG8_BAR; PG8_WAIT_L(0); PG8_MMA(0, 0, At, B0); PG8_BAR; PG8_SCHED;
;             PG8_LDB(B1, 1, 1); PG8_STAGE(PG8_SB(1, 0), b3, voffB);
;             PG8_BAR; PG8_WAIT_L(0); PG8_MMA(0, 1, At, B1); PG8_BAR;
;             PG8_LDA(At, 1, 1); PG8_STAGE(PG8_SA(1, 0), a3, voffA);
;             PG8_BAR; PG8_WAIT_L(0); PG8_MMA(1, 0, At, B0); PG8_BAR; PG8_SCHED;
	s_add_u32 s58, s14, 0x80000
	s_addc_u32 s59, s15, 0
	s_add_i32 s57, s60, s40
	v_lshl_add_u64 v[28:29], s[58:59], 0, v[2:3]
	s_mov_b32 m0, s57
	s_nop 0
	global_load_lds_dwordx4 v[28:29], off
	v_lshl_add_u64 v[28:29], s[58:59], 0, v[0:1]
	s_add_i32 m0, s57, 0x2000
	s_nop 0
	global_load_lds_dwordx4 v[28:29], off
	s_waitcnt vmcnt(6)
	s_barrier
	s_setprio 1
	v_mfma_f32_16x16x32_bf16 v[48:51], v[222:225], v[198:201], v[48:51]
	v_mfma_f32_16x16x32_bf16 v[44:47], v[230:233], v[198:201], v[44:47]
	v_mfma_f32_16x16x32_bf16 v[24:27], v[222:225], v[206:209], v[24:27]
	v_mfma_f32_16x16x32_bf16 v[20:23], v[230:233], v[206:209], v[20:23]
	v_mfma_f32_16x16x32_bf16 v[8:11], v[222:225], v[214:217], v[8:11]
	v_mfma_f32_16x16x32_bf16 v[4:7], v[230:233], v[214:217], v[4:7]
	v_mfma_f32_16x16x32_bf16 v[28:31], v[222:225], v[170:173], v[72:75]
	v_mfma_f32_16x16x32_bf16 v[32:35], v[230:233], v[170:173], v[68:71]
	v_mfma_f32_16x16x32_bf16 v[48:51], v[226:229], v[202:205], v[48:51]
	v_mfma_f32_16x16x32_bf16 v[44:47], v[234:237], v[202:205], v[44:47]
	v_mfma_f32_16x16x32_bf16 v[24:27], v[226:229], v[210:213], v[24:27]
	v_mfma_f32_16x16x32_bf16 v[20:23], v[234:237], v[210:213], v[20:23]
	v_mfma_f32_16x16x32_bf16 v[8:11], v[226:229], v[218:221], v[8:11]
	v_mfma_f32_16x16x32_bf16 v[4:7], v[234:237], v[218:221], v[4:7]
	v_mfma_f32_16x16x32_bf16 v[28:31], v[226:229], v[194:197], v[28:31]
	v_mfma_f32_16x16x32_bf16 v[32:35], v[234:237], v[194:197], v[32:35]
	s_setprio 0
	s_add_i32 s57, 0, 0x18000
	v_add_u32_e32 v72, s57, v190
	s_barrier
	ds_read_b128 v[60:63], v72
	ds_read_b128 v[64:67], v72 offset:1024
	ds_read_b128 v[68:71], v72 offset:2048
	ds_read_b128 v[72:75], v72 offset:3072
	s_add_u32 s18, s18, 0x80000
	s_addc_u32 s19, s19, 0
	s_mov_b32 m0, s43
	v_lshl_add_u64 v[222:223], s[18:19], 0, v[164:165]
	ds_read_b128 v[170:173], v192 offset:32768
	ds_read_b128 v[194:197], v192 offset:33792
	ds_read_b128 v[198:201], v192 offset:34816
	ds_read_b128 v[202:205], v192 offset:35840
	ds_read_b128 v[206:209], v192 offset:36864
	ds_read_b128 v[210:213], v192 offset:37888
	ds_read_b128 v[214:217], v192 offset:38912
	ds_read_b128 v[218:221], v192 offset:39936
	global_load_lds_dwordx4 v[222:223], off
	v_lshl_add_u64 v[222:223], s[18:19], 0, v[162:163]
	s_mov_b32 m0, s46
	s_nop 0
	global_load_lds_dwordx4 v[222:223], off
	s_waitcnt lgkmcnt(8)
	s_barrier
	s_waitcnt lgkmcnt(0)
	s_setprio 1
	s_waitcnt lgkmcnt(0)
	v_mfma_f32_16x16x32_bf16 v[144:147], v[60:63], v[170:173], v[144:147]
	v_mfma_f32_16x16x32_bf16 v[140:143], v[68:71], v[170:173], v[140:143]
	v_mfma_f32_16x16x32_bf16 v[128:131], v[60:63], v[198:201], v[128:131]
	v_mfma_f32_16x16x32_bf16 v[124:127], v[68:71], v[198:201], v[124:127]
	v_mfma_f32_16x16x32_bf16 v[112:115], v[60:63], v[206:209], v[112:115]
	v_mfma_f32_16x16x32_bf16 v[108:111], v[68:71], v[206:209], v[108:111]
	v_mfma_f32_16x16x32_bf16 v[96:99], v[60:63], v[214:217], v[96:99]
	v_mfma_f32_16x16x32_bf16 v[92:95], v[68:71], v[214:217], v[92:95]
	v_mfma_f32_16x16x32_bf16 v[144:147], v[64:67], v[194:197], v[144:147]
	v_mfma_f32_16x16x32_bf16 v[140:143], v[72:75], v[194:197], v[140:143]
	v_mfma_f32_16x16x32_bf16 v[128:131], v[64:67], v[202:205], v[128:131]
	v_mfma_f32_16x16x32_bf16 v[124:127], v[72:75], v[202:205], v[124:127]
	v_mfma_f32_16x16x32_bf16 v[112:115], v[64:67], v[210:213], v[112:115]
	v_mfma_f32_16x16x32_bf16 v[108:111], v[72:75], v[210:213], v[108:111]
	v_mfma_f32_16x16x32_bf16 v[96:99], v[64:67], v[218:221], v[96:99]
	v_mfma_f32_16x16x32_bf16 v[92:95], v[72:75], v[218:221], v[92:95]
	s_setprio 0
	s_barrier
	s_add_i32 s18, 0, 0x1c000
	s_add_i32 s19, s57, s40
	v_add_u32_e32 v193, s18, v190
	v_lshl_add_u64 v[174:175], v[174:175], 0, s[30:31]
	s_mov_b32 m0, s19
	ds_read_b128 v[222:225], v193
	ds_read_b128 v[226:229], v193 offset:1024
	ds_read_b128 v[230:233], v193 offset:2048
	ds_read_b128 v[234:237], v193 offset:3072
	global_load_lds_dwordx4 v[174:175], off
	v_lshl_add_u64 v[174:175], v[238:239], 0, s[30:31]
	s_add_i32 m0, s19, 0x2000
	s_nop 0
	global_load_lds_dwordx4 v[174:175], off
	s_barrier
	s_waitcnt lgkmcnt(0)
	s_setprio 1
	s_waitcnt lgkmcnt(0)
	v_mfma_f32_16x16x32_bf16 v[136:139], v[222:225], v[170:173], v[136:139]
	v_mfma_f32_16x16x32_bf16 v[132:135], v[230:233], v[170:173], v[132:135]
	v_mfma_f32_16x16x32_bf16 v[120:123], v[222:225], v[198:201], v[120:123]
	v_mfma_f32_16x16x32_bf16 v[116:119], v[230:233], v[198:201], v[116:119]
	v_mfma_f32_16x16x32_bf16 v[104:107], v[222:225], v[206:209], v[104:107]
	v_mfma_f32_16x16x32_bf16 v[100:103], v[230:233], v[206:209], v[100:103]
	v_mfma_f32_16x16x32_bf16 v[88:91], v[222:225], v[214:217], v[88:91]
	v_mfma_f32_16x16x32_bf16 v[84:87], v[230:233], v[214:217], v[84:87]
	v_mfma_f32_16x16x32_bf16 v[136:139], v[226:229], v[194:197], v[136:139]
	v_mfma_f32_16x16x32_bf16 v[132:135], v[234:237], v[194:197], v[132:135]
	v_mfma_f32_16x16x32_bf16 v[120:123], v[226:229], v[202:205], v[120:123]
	v_mfma_f32_16x16x32_bf16 v[116:119], v[234:237], v[202:205], v[116:119]
	v_mfma_f32_16x16x32_bf16 v[104:107], v[226:229], v[210:213], v[104:107]
	v_mfma_f32_16x16x32_bf16 v[100:103], v[234:237], v[210:213], v[100:103]
	v_mfma_f32_16x16x32_bf16 v[88:91], v[226:229], v[218:221], v[88:91]
	v_mfma_f32_16x16x32_bf16 v[84:87], v[234:237], v[218:221], v[84:87]
	s_setprio 0
	s_mov_b32 m0, s47
	v_lshl_add_u64 v[174:175], v[240:241], 0, s[30:31]
	s_barrier
	ds_read_b128 v[170:173], v192 offset:49152
	ds_read_b128 v[194:197], v192 offset:50176
	ds_read_b128 v[198:201], v192 offset:51200
	ds_read_b128 v[202:205], v192 offset:52224
	ds_read_b128 v[206:209], v192 offset:53248
	ds_read_b128 v[210:213], v192 offset:54272
	ds_read_b128 v[214:217], v192 offset:55296
	ds_read_b128 v[218:221], v192 offset:56320
	global_load_lds_dwordx4 v[174:175], off
	v_lshl_add_u64 v[174:175], v[242:243], 0, s[30:31]
	s_mov_b32 m0, s48
	s_nop 0
	global_load_lds_dwordx4 v[174:175], off
	s_barrier
; #define PG8_STAGE(bufoff, gbase, voff) do { _Pragma("unroll") for (int _i = 0; _i < 2; ++_i) \
;         __builtin_amdgcn_global_load_lds((const unsigned*)((const char*)(gbase) + (voff)[_i]), (LAS unsigned*)(lds + (bufoff) + ldsw + _i * 8192), 16, 0, 0); } while (0)
; #define PG8_WAIT_V(n) asm volatile("s_waitcnt vmcnt(" #n ")" ::: "memory")
; #define PG8_WAIT_L(n) asm volatile("s_waitcnt lgkmcnt(" #n ")" ::: "memory")
; #define PG8_BAR __builtin_amdgcn_s_barrier()
; #define PG8_SCHED __builtin_amdgcn_sched_barrier(0)
; template <class Epi>
; __device__ __forceinline__ void gemm_phase(LAS unsigned char* lds, const Gemm g, const StaticOrder& S, const Epi& E, const int tid) {
;     ...
;             PG8_BAR; PG8_WAIT_L(0); PG8_MMA(1, 0, At, B0); PG8_BAR; PG8_SCHED;
;             PG8_STAGE(PG8_SB(1, 1), b3 + hstepB, voffB);
;             PG8_WAIT_V(6); PG8_BAR; PG8_MMA(1, 1, At, B1); PG8_BAR;
;     __device__ __forceinline__ void operator()(const f32x4 (&acc)[2][2][4][2], const pg8::Unit& u, int wr, int wc, int fr, int fq) const {
;         const int row0 = u.pm * 256 + wr * 64 + fr, col0 = u.pn * 256 + wc * 32 + 8 * fq;
;         const float* gp = gate + (size_t)((u.pm * 256) >> 12) * 6144 + col0;
;         f32x4 gv[2][2];
; #pragma unroll
;         for (int bj = 0; bj < 2; ++bj)
; #pragma unroll
;             for (int n = 0; n < 2; ++n) gv[bj][n] = *(const f32x4*)(gp + bj * 128 + 4 * n);
; #pragma unroll
;         for (int ai = 0; ai < 2; ++ai)
; #pragma unroll
;             for (int m = 0; m < 4; ++m) { const size_t ro = (size_t)(row0 + ai * 128 + m * 16) * DM + col0;
; #pragma unroll
;                 for (int bj = 0; bj < 2; ++bj) {
;                     f32x4 x0, x1;
;                     if (XF32) { x0 = *(const f32x4*)(xin + ro + bj * 128); x1 = *(const f32x4*)(xin + ro + bj * 128 + 4); }
;                     else { const h8 xh = *(const h8*)(H + ro + bj * 128); x0 = (f32x4){(float)xh[0], (float)xh[1], (float)xh[2], (float)xh[3]}; x1 = (f32x4){(float)xh[4], (float)xh[5], (float)xh[6], (float)xh[7]}; }
;                     const f32x4 y0 = x0 + gv[bj][0] * acc[ai][bj][m][0], y1 = x1 + gv[bj][1] * acc[ai][bj][m][1];
	s_waitcnt lgkmcnt(0)
	s_setprio 1
	s_waitcnt lgkmcnt(0)
	v_mfma_f32_16x16x32_bf16 v[80:83], v[60:63], v[170:173], v[80:83]
	v_mfma_f32_16x16x32_bf16 v[76:79], v[68:71], v[170:173], v[76:79]
	v_mfma_f32_16x16x32_bf16 v[56:59], v[60:63], v[198:201], v[56:59]
	v_mfma_f32_16x16x32_bf16 v[52:55], v[68:71], v[198:201], v[52:55]
	v_mfma_f32_16x16x32_bf16 v[40:43], v[60:63], v[206:209], v[40:43]
	v_mfma_f32_16x16x32_bf16 v[36:39], v[68:71], v[206:209], v[36:39]
	v_mfma_f32_16x16x32_bf16 v[16:19], v[60:63], v[214:217], v[16:19]
	v_mfma_f32_16x16x32_bf16 v[12:15], v[68:71], v[214:217], v[12:15]
	v_mfma_f32_16x16x32_bf16 v[80:83], v[64:67], v[194:197], v[80:83]
	v_mfma_f32_16x16x32_bf16 v[76:79], v[72:75], v[194:197], v[76:79]
	v_mfma_f32_16x16x32_bf16 v[56:59], v[64:67], v[202:205], v[56:59]
	v_mfma_f32_16x16x32_bf16 v[52:55], v[72:75], v[202:205], v[52:55]
	v_mfma_f32_16x16x32_bf16 v[40:43], v[64:67], v[210:213], v[40:43]
	v_mfma_f32_16x16x32_bf16 v[36:39], v[72:75], v[210:213], v[36:39]
	v_mfma_f32_16x16x32_bf16 v[16:19], v[64:67], v[218:221], v[16:19]
	v_mfma_f32_16x16x32_bf16 v[12:15], v[72:75], v[218:221], v[12:15]
	s_setprio 0
	s_barrier
	s_add_u32 s14, s14, 0x80080
	s_addc_u32 s15, s15, 0
	s_add_i32 s18, s18, s40
	v_lshl_add_u64 v[60:61], s[14:15], 0, v[2:3]
	s_mov_b32 m0, s18
	s_nop 0
	global_load_lds_dwordx4 v[60:61], off
	v_lshl_add_u64 v[60:61], s[14:15], 0, v[0:1]
	s_add_i32 m0, s18, 0x2000
	s_nop 0
	global_load_lds_dwordx4 v[60:61], off
	s_waitcnt vmcnt(6)
	s_barrier
	s_setprio 1
	v_mfma_f32_16x16x32_bf16 v[28:31], v[222:225], v[170:173], v[28:31]
	v_mfma_f32_16x16x32_bf16 v[72:75], v[226:229], v[194:197], v[28:31]
	v_mfma_f32_16x16x32_bf16 v[28:31], v[230:233], v[170:173], v[32:35]
	v_mfma_f32_16x16x32_bf16 v[68:71], v[234:237], v[194:197], v[28:31]
	v_mfma_f32_16x16x32_bf16 v[28:31], v[222:225], v[198:201], v[48:51]
	v_mfma_f32_16x16x32_bf16 v[48:51], v[226:229], v[202:205], v[28:31]
	v_mfma_f32_16x16x32_bf16 v[28:31], v[230:233], v[198:201], v[44:47]
	v_mfma_f32_16x16x32_bf16 v[24:27], v[222:225], v[206:209], v[24:27]
	v_mfma_f32_16x16x32_bf16 v[20:23], v[230:233], v[206:209], v[20:23]
	v_mfma_f32_16x16x32_bf16 v[8:11], v[222:225], v[214:217], v[8:11]
	v_mfma_f32_16x16x32_bf16 v[4:7], v[230:233], v[214:217], v[4:7]
	v_mfma_f32_16x16x32_bf16 v[44:47], v[234:237], v[202:205], v[28:31]
	v_mfma_f32_16x16x32_bf16 v[24:27], v[226:229], v[210:213], v[24:27]
	v_mfma_f32_16x16x32_bf16 v[20:23], v[234:237], v[210:213], v[20:23]
	v_mfma_f32_16x16x32_bf16 v[8:11], v[226:229], v[218:221], v[8:11]
	v_mfma_f32_16x16x32_bf16 v[4:7], v[234:237], v[218:221], v[4:7]
	s_setprio 0
	s_add_i32 s56, s56, 2
	s_add_u32 s12, s12, 0x100
	s_addc_u32 s13, s13, 0
	s_add_u32 s54, s54, 0x100
	s_addc_u32 s55, s55, 0
	s_cmp_gt_u32 s56, 29
	s_barrier
	s_cbranch_scc0 .LBB0_660
	s_ashr_i32 s1, s50, 4
	v_lshl_add_u32 v172, s50, 8, v189
	v_lshl_or_b32 v170, s51, 8, v191
	s_mul_hi_i32 s7, s1, 0x6000
	s_mulk_i32 s1, 0x6000
	v_ashrrev_i32_e32 v173, 31, v172
	s_add_u32 s12, s23, s1
	v_ashrrev_i32_e32 v171, 31, v170
	v_lshlrev_b64 v[174:175], 12, v[172:173]
	s_addc_u32 s13, s24, s7
	v_lshl_add_u64 v[194:195], s[16:17], 0, v[174:175]
	v_lshlrev_b64 v[174:175], 1, v[170:171]
	v_lshl_add_u64 v[32:33], v[170:171], 2, s[12:13]
	v_lshl_add_u64 v[170:171], v[194:195], 0, v[174:175]
	global_load_dwordx4 v[60:63], v[32:33], off offset:16
	global_load_dwordx4 v[64:67], v[32:33], off
	global_load_dwordx4 v[28:31], v[32:33], off offset:528
	s_nop 0
	global_load_dwordx4 v[32:35], v[32:33], off offset:512
	v_add_co_u32_e32 v242, vcc, 0, v170
	s_nop 1
	v_addc_co_u32_e32 v243, vcc, 0, v171, vcc
	global_load_dwordx4 v[202:205], v[242:243], off
	v_add_co_u32_e32 v242, vcc, 0, v170
	s_nop 1
	v_addc_co_u32_e32 v243, vcc, 0, v171, vcc
	global_load_dwordx4 v[206:209], v[242:243], off offset:256
	v_add_co_u32_e32 v242, vcc, 0x10000, v170
	s_nop 1
	v_addc_co_u32_e32 v243, vcc, 0, v171, vcc
	global_load_dwordx4 v[210:213], v[242:243], off
	v_add_co_u32_e32 v242, vcc, 0x10000, v170
	s_nop 1
	v_addc_co_u32_e32 v243, vcc, 0, v171, vcc
	global_load_dwordx4 v[214:217], v[242:243], off offset:256
	v_add_co_u32_e32 v242, vcc, 0x20000, v170
	s_nop 1
	v_addc_co_u32_e32 v243, vcc, 0, v171, vcc
	global_load_dwordx4 v[218:221], v[242:243], off
	v_add_co_u32_e32 v242, vcc, 0x20000, v170
	s_nop 1
	v_addc_co_u32_e32 v243, vcc, 0, v171, vcc
	global_load_dwordx4 v[222:225], v[242:243], off offset:256
	v_add_co_u32_e32 v242, vcc, 0x30000, v170
	s_nop 1
	v_addc_co_u32_e32 v243, vcc, 0, v171, vcc
	global_load_dwordx4 v[226:229], v[242:243], off
	v_add_co_u32_e32 v242, vcc, 0x30000, v170
	s_nop 1
	v_addc_co_u32_e32 v243, vcc, 0, v171, vcc
	global_load_dwordx4 v[230:233], v[242:243], off offset:256
	v_add_co_u32_e32 v242, vcc, 0x80000, v170
	s_nop 1
	v_addc_co_u32_e32 v243, vcc, 0, v171, vcc
	global_load_dwordx4 v[234:237], v[242:243], off
	v_add_co_u32_e32 v242, vcc, 0x80000, v170
	s_nop 1
	v_addc_co_u32_e32 v243, vcc, 0, v171, vcc
	global_load_dwordx4 v[238:241], v[242:243], off offset:256
	v_add_co_u32_e32 v242, vcc, 0x90000, v170
	s_nop 1
	v_addc_co_u32_e32 v243, vcc, 0, v171, vcc
	global_load_dwordx4 v[244:247], v[242:243], off
	s_mov_b32 s1, 0x80000
	s_nop 1
	s_waitcnt vmcnt(10)
;     __device__ __forceinline__ void operator()(const f32x4 (&acc)[2][2][4][2], const pg8::Unit& u, int wr, int wc, int fr, int fq) const {
;     ...
;             for (int m = 0; m < 4; ++m) { const size_t ro = (size_t)(row0 + ai * 128 + m * 16) * DM + col0;
; #pragma unroll
;                 for (int bj = 0; bj < 2; ++bj) {
;                     f32x4 x0, x1;
;                     if (XF32) { x0 = *(const f32x4*)(xin + ro + bj * 128); x1 = *(const f32x4*)(xin + ro + bj * 128 + 4); }
;                     else { const h8 xh = *(const h8*)(H + ro + bj * 128); x0 = (f32x4){(float)xh[0], (float)xh[1], (float)xh[2], (float)xh[3]}; x1 = (f32x4){(float)xh[4], (float)xh[5], (float)xh[6], (float)xh[7]}; }
;                     const f32x4 y0 = x0 + gv[bj][0] * acc[ai][bj][m][0], y1 = x1 + gv[bj][1] * acc[ai][bj][m][1];
;                     h8 o; o[0] = (half_t)y0[0]; o[1] = (half_t)y0[1]; o[2] = (half_t)y0[2]; o[3] = (half_t)y0[3]; o[4] = (half_t)y1[0]; o[5] = (half_t)y1[1]; o[6] = (half_t)y1[2]; o[7] = (half_t)y1[3];
;                     *(h8*)(H + ro + bj * 128) = o; } }
;     }
	v_mov_b32_e32 v194, v202
	v_mov_b32_e32 v195, v203
	v_mov_b32_e32 v196, v204
	v_mov_b32_e32 v197, v205
	v_add_co_u32_e32 v242, vcc, 0x90000, v170
	s_nop 1
	v_addc_co_u32_e32 v243, vcc, 0, v171, vcc
	global_load_dwordx4 v[202:205], v[242:243], off offset:256
	s_mov_b64 s[12:13], 0x80000
	s_mov_b32 s51, s0
	s_mov_b32 s50, s6
	s_mov_b64 s[14:15], s[10:11]
	v_readlane_b32 s59, v251, 43
	s_nop 0
	v_cvt_f32_f16_e32 v198, v194
	v_cvt_f32_f16_sdwa v199, v194 dst_sel:DWORD dst_unused:UNUSED_PAD src0_sel:WORD_1
	v_cvt_f32_f16_e32 v194, v195
	v_cvt_f32_f16_sdwa v195, v195 dst_sel:DWORD dst_unused:UNUSED_PAD src0_sel:WORD_1
	v_cvt_f32_f16_e32 v200, v196
	v_cvt_f32_f16_sdwa v201, v196 dst_sel:DWORD dst_unused:UNUSED_PAD src0_sel:WORD_1
	v_cvt_f32_f16_e32 v196, v197
	v_cvt_f32_f16_sdwa v197, v197 dst_sel:DWORD dst_unused:UNUSED_PAD src0_sel:WORD_1
	v_pk_fma_f32 v[146:147], v[146:147], v[66:67], v[194:195]
	v_pk_fma_f32 v[144:145], v[144:145], v[64:65], v[198:199]
	v_pk_fma_f32 v[140:141], v[140:141], v[60:61], v[200:201]
	v_pk_fma_f32 v[142:143], v[142:143], v[62:63], v[196:197]
	s_nop 0
	v_cvt_pk_f16_f32 v143, v142, v143
	v_cvt_pk_f16_f32 v142, v140, v141
	v_cvt_pk_f16_f32 v141, v146, v147
	v_cvt_pk_f16_f32 v140, v144, v145
	global_store_dwordx4 v[170:171], v[140:143], off
	s_nop 1
	s_waitcnt vmcnt(10)
	v_mov_b32_e32 v140, v206
	v_mov_b32_e32 v141, v207
	v_mov_b32_e32 v142, v208
	v_mov_b32_e32 v143, v209
	v_add_co_u32_e32 v242, vcc, 0xa0000, v170
	s_nop 1
	v_addc_co_u32_e32 v243, vcc, 0, v171, vcc
	global_load_dwordx4 v[206:209], v[242:243], off
	s_nop 0
	v_cvt_f32_f16_e32 v144, v140
	v_cvt_f32_f16_sdwa v145, v140 dst_sel:DWORD dst_unused:UNUSED_PAD src0_sel:WORD_1
	v_cvt_f32_f16_e32 v140, v141
	v_cvt_f32_f16_sdwa v141, v141 dst_sel:DWORD dst_unused:UNUSED_PAD src0_sel:WORD_1
	v_cvt_f32_f16_e32 v146, v142
	v_cvt_f32_f16_sdwa v147, v142 dst_sel:DWORD dst_unused:UNUSED_PAD src0_sel:WORD_1
	v_cvt_f32_f16_e32 v142, v143
	v_cvt_f32_f16_sdwa v143, v143 dst_sel:DWORD dst_unused:UNUSED_PAD src0_sel:WORD_1
	v_pk_fma_f32 v[138:139], v[138:139], v[34:35], v[140:141]
	v_pk_fma_f32 v[136:137], v[136:137], v[32:33], v[144:145]
	v_pk_fma_f32 v[132:133], v[132:133], v[28:29], v[146:147]
	v_pk_fma_f32 v[134:135], v[134:135], v[30:31], v[142:143]
	s_nop 0
	v_cvt_pk_f16_f32 v135, v134, v135
	v_cvt_pk_f16_f32 v134, v132, v133
	v_cvt_pk_f16_f32 v133, v138, v139
	v_cvt_pk_f16_f32 v132, v136, v137
	global_store_dwordx4 v[170:171], v[132:135], off offset:256
	s_nop 1
	v_or_b32_e32 v132, 16, v172
	v_ashrrev_i32_e32 v133, 31, v132
	v_lshlrev_b64 v[132:133], 12, v[132:133]
	v_lshl_add_u64 v[132:133], s[16:17], 0, v[132:133]
	v_lshl_add_u64 v[136:137], v[132:133], 0, v[174:175]
	s_nop 1
	s_waitcnt vmcnt(10)
	v_mov_b32_e32 v132, v210
	v_mov_b32_e32 v133, v211
	v_mov_b32_e32 v134, v212
	v_mov_b32_e32 v135, v213
	v_add_co_u32_e32 v242, vcc, 0xa0000, v170
	s_nop 1
	v_addc_co_u32_e32 v243, vcc, 0, v171, vcc
	global_load_dwordx4 v[210:213], v[242:243], off offset:256
	s_nop 0
	v_cvt_f32_f16_e32 v138, v132
	v_cvt_f32_f16_sdwa v139, v132 dst_sel:DWORD dst_unused:UNUSED_PAD src0_sel:WORD_1
	v_cvt_f32_f16_e32 v132, v133
	v_cvt_f32_f16_sdwa v133, v133 dst_sel:DWORD dst_unused:UNUSED_PAD src0_sel:WORD_1
	v_cvt_f32_f16_e32 v140, v134
	v_cvt_f32_f16_sdwa v141, v134 dst_sel:DWORD dst_unused:UNUSED_PAD src0_sel:WORD_1
	v_cvt_f32_f16_e32 v134, v135
	v_cvt_f32_f16_sdwa v135, v135 dst_sel:DWORD dst_unused:UNUSED_PAD src0_sel:WORD_1
	v_pk_fma_f32 v[130:131], v[130:131], v[66:67], v[132:133]
	v_pk_fma_f32 v[128:129], v[128:129], v[64:65], v[138:139]
	v_pk_fma_f32 v[124:125], v[124:125], v[60:61], v[140:141]
	v_pk_fma_f32 v[126:127], v[126:127], v[62:63], v[134:135]
	s_nop 0
	v_cvt_pk_f16_f32 v127, v126, v127
	v_cvt_pk_f16_f32 v126, v124, v125
	v_cvt_pk_f16_f32 v125, v130, v131
	v_cvt_pk_f16_f32 v124, v128, v129
	global_store_dwordx4 v[136:137], v[124:127], off
	s_nop 1
	s_waitcnt vmcnt(10)
	v_mov_b32_e32 v124, v214
	v_mov_b32_e32 v125, v215
	v_mov_b32_e32 v126, v216
	v_mov_b32_e32 v127, v217
	v_add_co_u32_e32 v242, vcc, 0xb0000, v170
	s_nop 1
	v_addc_co_u32_e32 v243, vcc, 0, v171, vcc
	global_load_dwordx4 v[214:217], v[242:243], off
	s_nop 0
	v_cvt_f32_f16_e32 v128, v124
	v_cvt_f32_f16_sdwa v129, v124 dst_sel:DWORD dst_unused:UNUSED_PAD src0_sel:WORD_1
	v_cvt_f32_f16_e32 v124, v125
	v_cvt_f32_f16_sdwa v125, v125 dst_sel:DWORD dst_unused:UNUSED_PAD src0_sel:WORD_1
	v_cvt_f32_f16_e32 v130, v126
	v_cvt_f32_f16_sdwa v131, v126 dst_sel:DWORD dst_unused:UNUSED_PAD src0_sel:WORD_1
	v_cvt_f32_f16_e32 v126, v127
	v_cvt_f32_f16_sdwa v127, v127 dst_sel:DWORD dst_unused:UNUSED_PAD src0_sel:WORD_1
	v_pk_fma_f32 v[122:123], v[122:123], v[34:35], v[124:125]
	v_pk_fma_f32 v[120:121], v[120:121], v[32:33], v[128:129]
	v_pk_fma_f32 v[116:117], v[116:117], v[28:29], v[130:131]
	v_pk_fma_f32 v[118:119], v[118:119], v[30:31], v[126:127]
	s_nop 0
	v_cvt_pk_f16_f32 v119, v118, v119
	v_cvt_pk_f16_f32 v118, v116, v117
	v_cvt_pk_f16_f32 v117, v122, v123
	v_cvt_pk_f16_f32 v116, v120, v121
	global_store_dwordx4 v[136:137], v[116:119], off offset:256
	s_nop 1
	v_or_b32_e32 v116, 32, v172
	v_ashrrev_i32_e32 v117, 31, v116
	v_lshlrev_b64 v[116:117], 12, v[116:117]
	v_lshl_add_u64 v[116:117], s[16:17], 0, v[116:117]
	v_lshl_add_u64 v[120:121], v[116:117], 0, v[174:175]
	s_nop 1
	s_waitcnt vmcnt(10)
;     __device__ __forceinline__ void operator()(const f32x4 (&acc)[2][2][4][2], const pg8::Unit& u, int wr, int wc, int fr, int fq) const {
;     ...
;             for (int m = 0; m < 4; ++m) { const size_t ro = (size_t)(row0 + ai * 128 + m * 16) * DM + col0;
; #pragma unroll
;                 for (int bj = 0; bj < 2; ++bj) {
;                     f32x4 x0, x1;
;                     if (XF32) { x0 = *(const f32x4*)(xin + ro + bj * 128); x1 = *(const f32x4*)(xin + ro + bj * 128 + 4); }
;                     else { const h8 xh = *(const h8*)(H + ro + bj * 128); x0 = (f32x4){(float)xh[0], (float)xh[1], (float)xh[2], (float)xh[3]}; x1 = (f32x4){(float)xh[4], (float)xh[5], (float)xh[6], (float)xh[7]}; }
;                     const f32x4 y0 = x0 + gv[bj][0] * acc[ai][bj][m][0], y1 = x1 + gv[bj][1] * acc[ai][bj][m][1];
;                     h8 o; o[0] = (half_t)y0[0]; o[1] = (half_t)y0[1]; o[2] = (half_t)y0[2]; o[3] = (half_t)y0[3]; o[4] = (half_t)y1[0]; o[5] = (half_t)y1[1]; o[6] = (half_t)y1[2]; o[7] = (half_t)y1[3];
;                     *(h8*)(H + ro + bj * 128) = o; } }
;     }
	v_mov_b32_e32 v116, v218
	v_mov_b32_e32 v117, v219
	v_mov_b32_e32 v118, v220
	v_mov_b32_e32 v119, v221
	v_add_co_u32_e32 v242, vcc, 0xb0000, v170
	s_nop 1
	v_addc_co_u32_e32 v243, vcc, 0, v171, vcc
	global_load_dwordx4 v[218:221], v[242:243], off offset:256
	s_nop 0
	v_cvt_f32_f16_e32 v122, v116
	v_cvt_f32_f16_sdwa v123, v116 dst_sel:DWORD dst_unused:UNUSED_PAD src0_sel:WORD_1
	v_cvt_f32_f16_e32 v116, v117
	v_cvt_f32_f16_sdwa v117, v117 dst_sel:DWORD dst_unused:UNUSED_PAD src0_sel:WORD_1
	v_cvt_f32_f16_e32 v124, v118
	v_cvt_f32_f16_sdwa v125, v118 dst_sel:DWORD dst_unused:UNUSED_PAD src0_sel:WORD_1
	v_cvt_f32_f16_e32 v118, v119
	v_cvt_f32_f16_sdwa v119, v119 dst_sel:DWORD dst_unused:UNUSED_PAD src0_sel:WORD_1
	v_pk_fma_f32 v[114:115], v[114:115], v[66:67], v[116:117]
	v_pk_fma_f32 v[112:113], v[112:113], v[64:65], v[122:123]
	v_pk_fma_f32 v[108:109], v[108:109], v[60:61], v[124:125]
	v_pk_fma_f32 v[110:111], v[110:111], v[62:63], v[118:119]
	s_nop 0
	v_cvt_pk_f16_f32 v111, v110, v111
	v_cvt_pk_f16_f32 v110, v108, v109
	v_cvt_pk_f16_f32 v109, v114, v115
	v_cvt_pk_f16_f32 v108, v112, v113
	global_store_dwordx4 v[120:121], v[108:111], off
	s_nop 1
	s_waitcnt vmcnt(10)
	v_mov_b32_e32 v108, v222
	v_mov_b32_e32 v109, v223
	v_mov_b32_e32 v110, v224
	v_mov_b32_e32 v111, v225
	s_nop 0
	v_cvt_f32_f16_e32 v112, v108
	v_cvt_f32_f16_sdwa v113, v108 dst_sel:DWORD dst_unused:UNUSED_PAD src0_sel:WORD_1
	v_cvt_f32_f16_e32 v108, v109
	v_cvt_f32_f16_sdwa v109, v109 dst_sel:DWORD dst_unused:UNUSED_PAD src0_sel:WORD_1
	v_cvt_f32_f16_e32 v114, v110
	v_cvt_f32_f16_sdwa v115, v110 dst_sel:DWORD dst_unused:UNUSED_PAD src0_sel:WORD_1
	v_cvt_f32_f16_e32 v110, v111
	v_cvt_f32_f16_sdwa v111, v111 dst_sel:DWORD dst_unused:UNUSED_PAD src0_sel:WORD_1
	v_pk_fma_f32 v[106:107], v[106:107], v[34:35], v[108:109]
	v_pk_fma_f32 v[104:105], v[104:105], v[32:33], v[112:113]
	v_pk_fma_f32 v[100:101], v[100:101], v[28:29], v[114:115]
	v_pk_fma_f32 v[102:103], v[102:103], v[30:31], v[110:111]
	s_nop 0
	v_cvt_pk_f16_f32 v103, v102, v103
	v_cvt_pk_f16_f32 v102, v100, v101
	v_cvt_pk_f16_f32 v101, v106, v107
	v_cvt_pk_f16_f32 v100, v104, v105
	global_store_dwordx4 v[120:121], v[100:103], off offset:256
	s_nop 1
	v_or_b32_e32 v100, 48, v172
	v_ashrrev_i32_e32 v101, 31, v100
	v_lshlrev_b64 v[100:101], 12, v[100:101]
	v_lshl_add_u64 v[100:101], s[16:17], 0, v[100:101]
	v_lshl_add_u64 v[104:105], v[100:101], 0, v[174:175]
	s_nop 1
	s_waitcnt vmcnt(9)
	v_mov_b32_e32 v100, v226
	v_mov_b32_e32 v101, v227
	v_mov_b32_e32 v102, v228
	v_mov_b32_e32 v103, v229
	s_nop 0
	v_cvt_f32_f16_e32 v106, v100
	v_cvt_f32_f16_sdwa v107, v100 dst_sel:DWORD dst_unused:UNUSED_PAD src0_sel:WORD_1
	v_cvt_f32_f16_e32 v100, v101
	v_cvt_f32_f16_sdwa v101, v101 dst_sel:DWORD dst_unused:UNUSED_PAD src0_sel:WORD_1
	v_cvt_f32_f16_e32 v108, v102
	v_cvt_f32_f16_sdwa v109, v102 dst_sel:DWORD dst_unused:UNUSED_PAD src0_sel:WORD_1
	v_cvt_f32_f16_e32 v102, v103
	v_cvt_f32_f16_sdwa v103, v103 dst_sel:DWORD dst_unused:UNUSED_PAD src0_sel:WORD_1
	v_pk_fma_f32 v[98:99], v[98:99], v[66:67], v[100:101]
	v_pk_fma_f32 v[96:97], v[96:97], v[64:65], v[106:107]
	v_pk_fma_f32 v[92:93], v[92:93], v[60:61], v[108:109]
	v_pk_fma_f32 v[94:95], v[94:95], v[62:63], v[102:103]
	s_nop 0
	v_cvt_pk_f16_f32 v95, v94, v95
	v_cvt_pk_f16_f32 v94, v92, v93
	v_cvt_pk_f16_f32 v93, v98, v99
	v_cvt_pk_f16_f32 v92, v96, v97
	global_store_dwordx4 v[104:105], v[92:95], off
	s_nop 1
	s_waitcnt vmcnt(8)
	v_mov_b32_e32 v92, v230
	v_mov_b32_e32 v93, v231
	v_mov_b32_e32 v94, v232
	v_mov_b32_e32 v95, v233
	s_nop 0
	v_cvt_f32_f16_e32 v96, v92
	v_cvt_f32_f16_sdwa v97, v92 dst_sel:DWORD dst_unused:UNUSED_PAD src0_sel:WORD_1
	v_cvt_f32_f16_e32 v92, v93
	v_cvt_f32_f16_sdwa v93, v93 dst_sel:DWORD dst_unused:UNUSED_PAD src0_sel:WORD_1
	v_cvt_f32_f16_e32 v98, v94
	v_cvt_f32_f16_sdwa v99, v94 dst_sel:DWORD dst_unused:UNUSED_PAD src0_sel:WORD_1
	v_cvt_f32_f16_e32 v94, v95
	v_cvt_f32_f16_sdwa v95, v95 dst_sel:DWORD dst_unused:UNUSED_PAD src0_sel:WORD_1
	v_pk_fma_f32 v[90:91], v[90:91], v[34:35], v[92:93]
	v_pk_fma_f32 v[84:85], v[84:85], v[28:29], v[98:99]
	v_pk_fma_f32 v[88:89], v[88:89], v[32:33], v[96:97]
	v_pk_fma_f32 v[86:87], v[86:87], v[30:31], v[94:95]
	s_nop 0
	v_cvt_pk_f16_f32 v87, v86, v87
	v_cvt_pk_f16_f32 v86, v84, v85
	v_cvt_pk_f16_f32 v85, v90, v91
	v_add_co_u32_e32 v90, vcc, s1, v170
	v_cvt_pk_f16_f32 v84, v88, v89
	s_nop 0
	v_addc_co_u32_e32 v91, vcc, 0, v171, vcc
	global_store_dwordx4 v[104:105], v[84:87], off offset:256
	s_nop 1
	s_waitcnt vmcnt(7)
	v_mov_b32_e32 v86, v234
	v_mov_b32_e32 v87, v235
	v_mov_b32_e32 v88, v236
	v_mov_b32_e32 v89, v237
	s_mov_b32 s1, 0x90000
	v_lshl_add_u64 v[84:85], v[170:171], 0, s[12:13]
	s_mov_b64 s[12:13], 0x90000
	s_nop 0
	v_cvt_f32_f16_e32 v92, v86
	v_cvt_f32_f16_sdwa v93, v86 dst_sel:DWORD dst_unused:UNUSED_PAD src0_sel:WORD_1
	v_cvt_f32_f16_e32 v86, v87
	v_cvt_f32_f16_sdwa v87, v87 dst_sel:DWORD dst_unused:UNUSED_PAD src0_sel:WORD_1
	v_cvt_f32_f16_e32 v94, v88
	v_cvt_f32_f16_sdwa v95, v88 dst_sel:DWORD dst_unused:UNUSED_PAD src0_sel:WORD_1
	v_cvt_f32_f16_e32 v88, v89
	v_cvt_f32_f16_sdwa v89, v89 dst_sel:DWORD dst_unused:UNUSED_PAD src0_sel:WORD_1
	v_pk_fma_f32 v[82:83], v[82:83], v[66:67], v[86:87]
	v_pk_fma_f32 v[80:81], v[80:81], v[64:65], v[92:93]
	v_pk_fma_f32 v[76:77], v[76:77], v[60:61], v[94:95]
	v_pk_fma_f32 v[78:79], v[78:79], v[62:63], v[88:89]
	s_nop 0
	v_cvt_pk_f16_f32 v79, v78, v79
	v_cvt_pk_f16_f32 v78, v76, v77
	v_cvt_pk_f16_f32 v77, v82, v83
	v_cvt_pk_f16_f32 v76, v80, v81
	global_store_dwordx4 v[90:91], v[76:79], off
	s_nop 1
	s_waitcnt vmcnt(6)
;     __device__ __forceinline__ void operator()(const f32x4 (&acc)[2][2][4][2], const pg8::Unit& u, int wr, int wc, int fr, int fq) const {
;     ...
;             for (int m = 0; m < 4; ++m) { const size_t ro = (size_t)(row0 + ai * 128 + m * 16) * DM + col0;
; #pragma unroll
;                 for (int bj = 0; bj < 2; ++bj) {
;                     f32x4 x0, x1;
;                     if (XF32) { x0 = *(const f32x4*)(xin + ro + bj * 128); x1 = *(const f32x4*)(xin + ro + bj * 128 + 4); }
;                     else { const h8 xh = *(const h8*)(H + ro + bj * 128); x0 = (f32x4){(float)xh[0], (float)xh[1], (float)xh[2], (float)xh[3]}; x1 = (f32x4){(float)xh[4], (float)xh[5], (float)xh[6], (float)xh[7]}; }
;                     const f32x4 y0 = x0 + gv[bj][0] * acc[ai][bj][m][0], y1 = x1 + gv[bj][1] * acc[ai][bj][m][1];
;                     h8 o; o[0] = (half_t)y0[0]; o[1] = (half_t)y0[1]; o[2] = (half_t)y0[2]; o[3] = (half_t)y0[3]; o[4] = (half_t)y1[0]; o[5] = (half_t)y1[1]; o[6] = (half_t)y1[2]; o[7] = (half_t)y1[3];
;                     *(h8*)(H + ro + bj * 128) = o; } }
;     }
	v_mov_b32_e32 v76, v238
	v_mov_b32_e32 v77, v239
	v_mov_b32_e32 v78, v240
	v_mov_b32_e32 v79, v241
	s_nop 0
	v_cvt_f32_f16_e32 v80, v76
	v_cvt_f32_f16_sdwa v81, v76 dst_sel:DWORD dst_unused:UNUSED_PAD src0_sel:WORD_1
	v_cvt_f32_f16_e32 v76, v77
	v_cvt_f32_f16_sdwa v77, v77 dst_sel:DWORD dst_unused:UNUSED_PAD src0_sel:WORD_1
	v_cvt_f32_f16_e32 v82, v78
	v_cvt_f32_f16_sdwa v83, v78 dst_sel:DWORD dst_unused:UNUSED_PAD src0_sel:WORD_1
	v_cvt_f32_f16_e32 v78, v79
	v_cvt_f32_f16_sdwa v79, v79 dst_sel:DWORD dst_unused:UNUSED_PAD src0_sel:WORD_1
	v_pk_fma_f32 v[74:75], v[74:75], v[34:35], v[76:77]
	v_pk_fma_f32 v[68:69], v[68:69], v[28:29], v[82:83]
	v_pk_fma_f32 v[72:73], v[72:73], v[32:33], v[80:81]
	v_pk_fma_f32 v[70:71], v[70:71], v[30:31], v[78:79]
	s_nop 0
	v_cvt_pk_f16_f32 v71, v70, v71
	v_cvt_pk_f16_f32 v70, v68, v69
	v_cvt_pk_f16_f32 v69, v74, v75
	v_add_co_u32_e32 v74, vcc, s1, v170
	v_cvt_pk_f16_f32 v68, v72, v73
	s_nop 0
	v_addc_co_u32_e32 v75, vcc, 0, v171, vcc
	global_store_dwordx4 v[84:85], v[68:71], off offset:256
	s_nop 1
	s_waitcnt vmcnt(5)
	v_mov_b32_e32 v70, v244
	v_mov_b32_e32 v71, v245
	v_mov_b32_e32 v72, v246
	v_mov_b32_e32 v73, v247
	s_mov_b32 s1, 0xa0000
	v_lshl_add_u64 v[68:69], v[170:171], 0, s[12:13]
	s_mov_b64 s[12:13], 0xa0000
	s_nop 0
	v_cvt_f32_f16_e32 v76, v70
	v_cvt_f32_f16_sdwa v77, v70 dst_sel:DWORD dst_unused:UNUSED_PAD src0_sel:WORD_1
	v_cvt_f32_f16_e32 v70, v71
	v_cvt_f32_f16_sdwa v71, v71 dst_sel:DWORD dst_unused:UNUSED_PAD src0_sel:WORD_1
	v_cvt_f32_f16_e32 v78, v72
	v_cvt_f32_f16_sdwa v79, v72 dst_sel:DWORD dst_unused:UNUSED_PAD src0_sel:WORD_1
	v_cvt_f32_f16_e32 v72, v73
	v_cvt_f32_f16_sdwa v73, v73 dst_sel:DWORD dst_unused:UNUSED_PAD src0_sel:WORD_1
	v_pk_fma_f32 v[58:59], v[58:59], v[66:67], v[70:71]
	v_pk_fma_f32 v[56:57], v[56:57], v[64:65], v[76:77]
	v_pk_fma_f32 v[52:53], v[52:53], v[60:61], v[78:79]
	v_pk_fma_f32 v[54:55], v[54:55], v[62:63], v[72:73]
	s_nop 0
	v_cvt_pk_f16_f32 v55, v54, v55
	v_cvt_pk_f16_f32 v54, v52, v53
	v_cvt_pk_f16_f32 v53, v58, v59
	v_cvt_pk_f16_f32 v52, v56, v57
	global_store_dwordx4 v[74:75], v[52:55], off
	s_nop 1
	s_waitcnt vmcnt(4)
	v_mov_b32_e32 v52, v202
	v_mov_b32_e32 v53, v203
	v_mov_b32_e32 v54, v204
	v_mov_b32_e32 v55, v205
	s_nop 0
	v_cvt_f32_f16_e32 v56, v52
	v_cvt_f32_f16_sdwa v57, v52 dst_sel:DWORD dst_unused:UNUSED_PAD src0_sel:WORD_1
	v_cvt_f32_f16_e32 v52, v53
	v_cvt_f32_f16_sdwa v53, v53 dst_sel:DWORD dst_unused:UNUSED_PAD src0_sel:WORD_1
	v_cvt_f32_f16_e32 v58, v54
	v_cvt_f32_f16_sdwa v59, v54 dst_sel:DWORD dst_unused:UNUSED_PAD src0_sel:WORD_1
	v_cvt_f32_f16_e32 v54, v55
	v_cvt_f32_f16_sdwa v55, v55 dst_sel:DWORD dst_unused:UNUSED_PAD src0_sel:WORD_1
	v_pk_fma_f32 v[50:51], v[50:51], v[34:35], v[52:53]
	v_pk_fma_f32 v[44:45], v[44:45], v[28:29], v[58:59]
	v_pk_fma_f32 v[48:49], v[48:49], v[32:33], v[56:57]
	v_pk_fma_f32 v[46:47], v[46:47], v[30:31], v[54:55]
	s_nop 0
	v_cvt_pk_f16_f32 v47, v46, v47
	v_cvt_pk_f16_f32 v46, v44, v45
	v_cvt_pk_f16_f32 v45, v50, v51
	v_add_co_u32_e32 v50, vcc, s1, v170
	v_cvt_pk_f16_f32 v44, v48, v49
	s_nop 0
	v_addc_co_u32_e32 v51, vcc, 0, v171, vcc
	global_store_dwordx4 v[68:69], v[44:47], off offset:256
	s_nop 1
	s_waitcnt vmcnt(3)
	v_mov_b32_e32 v46, v206
	v_mov_b32_e32 v47, v207
	v_mov_b32_e32 v48, v208
	v_mov_b32_e32 v49, v209
	s_mov_b32 s1, 0xb0000
	v_lshl_add_u64 v[44:45], v[170:171], 0, s[12:13]
	s_mov_b64 s[12:13], 0xb0000
	s_nop 0
	v_cvt_f32_f16_e32 v52, v46
	v_cvt_f32_f16_sdwa v53, v46 dst_sel:DWORD dst_unused:UNUSED_PAD src0_sel:WORD_1
	v_cvt_f32_f16_e32 v46, v47
	v_cvt_f32_f16_sdwa v47, v47 dst_sel:DWORD dst_unused:UNUSED_PAD src0_sel:WORD_1
	v_cvt_f32_f16_e32 v54, v48
	v_cvt_f32_f16_sdwa v55, v48 dst_sel:DWORD dst_unused:UNUSED_PAD src0_sel:WORD_1
	v_cvt_f32_f16_e32 v48, v49
	v_cvt_f32_f16_sdwa v49, v49 dst_sel:DWORD dst_unused:UNUSED_PAD src0_sel:WORD_1
	v_pk_fma_f32 v[42:43], v[42:43], v[66:67], v[46:47]
	v_pk_fma_f32 v[40:41], v[40:41], v[64:65], v[52:53]
	v_pk_fma_f32 v[36:37], v[36:37], v[60:61], v[54:55]
	v_pk_fma_f32 v[38:39], v[38:39], v[62:63], v[48:49]
	s_nop 0
	v_cvt_pk_f16_f32 v39, v38, v39
	v_cvt_pk_f16_f32 v38, v36, v37
	v_cvt_pk_f16_f32 v37, v42, v43
	v_cvt_pk_f16_f32 v36, v40, v41
	global_store_dwordx4 v[50:51], v[36:39], off
	s_nop 1
	s_waitcnt vmcnt(2)
;     __device__ __forceinline__ void operator()(const f32x4 (&acc)[2][2][4][2], const pg8::Unit& u, int wr, int wc, int fr, int fq) const {
;     ...
;             for (int m = 0; m < 4; ++m) { const size_t ro = (size_t)(row0 + ai * 128 + m * 16) * DM + col0;
; #pragma unroll
;                 for (int bj = 0; bj < 2; ++bj) {
;                     f32x4 x0, x1;
;                     if (XF32) { x0 = *(const f32x4*)(xin + ro + bj * 128); x1 = *(const f32x4*)(xin + ro + bj * 128 + 4); }
;                     else { const h8 xh = *(const h8*)(H + ro + bj * 128); x0 = (f32x4){(float)xh[0], (float)xh[1], (float)xh[2], (float)xh[3]}; x1 = (f32x4){(float)xh[4], (float)xh[5], (float)xh[6], (float)xh[7]}; }
;                     const f32x4 y0 = x0 + gv[bj][0] * acc[ai][bj][m][0], y1 = x1 + gv[bj][1] * acc[ai][bj][m][1];
;                     h8 o; o[0] = (half_t)y0[0]; o[1] = (half_t)y0[1]; o[2] = (half_t)y0[2]; o[3] = (half_t)y0[3]; o[4] = (half_t)y1[0]; o[5] = (half_t)y1[1]; o[6] = (half_t)y1[2]; o[7] = (half_t)y1[3];
;                     *(h8*)(H + ro + bj * 128) = o; } }
;     }
	v_mov_b32_e32 v36, v210
	v_mov_b32_e32 v37, v211
	v_mov_b32_e32 v38, v212
	v_mov_b32_e32 v39, v213
	s_nop 0
	v_cvt_f32_f16_e32 v40, v36
	v_cvt_f32_f16_sdwa v41, v36 dst_sel:DWORD dst_unused:UNUSED_PAD src0_sel:WORD_1
	v_cvt_f32_f16_e32 v36, v37
	v_cvt_f32_f16_sdwa v37, v37 dst_sel:DWORD dst_unused:UNUSED_PAD src0_sel:WORD_1
	v_cvt_f32_f16_e32 v42, v38
	v_cvt_f32_f16_sdwa v43, v38 dst_sel:DWORD dst_unused:UNUSED_PAD src0_sel:WORD_1
	v_cvt_f32_f16_e32 v38, v39
	v_cvt_f32_f16_sdwa v39, v39 dst_sel:DWORD dst_unused:UNUSED_PAD src0_sel:WORD_1
	v_pk_fma_f32 v[26:27], v[26:27], v[34:35], v[36:37]
	v_pk_fma_f32 v[20:21], v[20:21], v[28:29], v[42:43]
	v_pk_fma_f32 v[24:25], v[24:25], v[32:33], v[40:41]
	v_pk_fma_f32 v[22:23], v[22:23], v[30:31], v[38:39]
	s_nop 0
	v_cvt_pk_f16_f32 v23, v22, v23
	v_cvt_pk_f16_f32 v22, v20, v21
	v_cvt_pk_f16_f32 v21, v26, v27
	v_add_co_u32_e32 v26, vcc, s1, v170
	v_cvt_pk_f16_f32 v20, v24, v25
	s_nop 0
	v_addc_co_u32_e32 v27, vcc, 0, v171, vcc
	global_store_dwordx4 v[44:45], v[20:23], off offset:256
	s_nop 1
	s_waitcnt vmcnt(1)
	v_mov_b32_e32 v22, v214
	v_mov_b32_e32 v23, v215
	v_mov_b32_e32 v24, v216
	v_mov_b32_e32 v25, v217
	s_and_b64 vcc, exec, s[4:5]
	v_lshl_add_u64 v[20:21], v[170:171], 0, s[12:13]
	s_mov_b64 s[12:13], s[8:9]
	s_nop 0
	v_cvt_f32_f16_e32 v36, v22
	v_cvt_f32_f16_sdwa v37, v22 dst_sel:DWORD dst_unused:UNUSED_PAD src0_sel:WORD_1
	v_cvt_f32_f16_e32 v22, v23
	v_cvt_f32_f16_sdwa v23, v23 dst_sel:DWORD dst_unused:UNUSED_PAD src0_sel:WORD_1
	v_cvt_f32_f16_e32 v38, v24
	v_cvt_f32_f16_sdwa v39, v24 dst_sel:DWORD dst_unused:UNUSED_PAD src0_sel:WORD_1
	v_cvt_f32_f16_e32 v24, v25
	v_cvt_f32_f16_sdwa v25, v25 dst_sel:DWORD dst_unused:UNUSED_PAD src0_sel:WORD_1
	v_pk_fma_f32 v[18:19], v[18:19], v[66:67], v[22:23]
	v_pk_fma_f32 v[16:17], v[16:17], v[64:65], v[36:37]
	v_pk_fma_f32 v[12:13], v[12:13], v[60:61], v[38:39]
	v_pk_fma_f32 v[14:15], v[14:15], v[62:63], v[24:25]
	s_nop 0
	v_cvt_pk_f16_f32 v15, v14, v15
	v_cvt_pk_f16_f32 v14, v12, v13
	v_cvt_pk_f16_f32 v13, v18, v19
	v_cvt_pk_f16_f32 v12, v16, v17
	global_store_dwordx4 v[26:27], v[12:15], off
	s_nop 1
	s_waitcnt vmcnt(0)
	v_mov_b32_e32 v12, v218
	v_mov_b32_e32 v13, v219
	v_mov_b32_e32 v14, v220
	v_mov_b32_e32 v15, v221
	s_nop 0
	v_cvt_f32_f16_e32 v16, v12
	v_cvt_f32_f16_sdwa v17, v12 dst_sel:DWORD dst_unused:UNUSED_PAD src0_sel:WORD_1
	v_cvt_f32_f16_e32 v12, v13
	v_cvt_f32_f16_sdwa v13, v13 dst_sel:DWORD dst_unused:UNUSED_PAD src0_sel:WORD_1
	v_cvt_f32_f16_e32 v18, v14
	v_cvt_f32_f16_sdwa v19, v14 dst_sel:DWORD dst_unused:UNUSED_PAD src0_sel:WORD_1
	v_cvt_f32_f16_e32 v14, v15
	v_cvt_f32_f16_sdwa v15, v15 dst_sel:DWORD dst_unused:UNUSED_PAD src0_sel:WORD_1
	v_pk_fma_f32 v[10:11], v[10:11], v[34:35], v[12:13]
	v_pk_fma_f32 v[8:9], v[8:9], v[32:33], v[16:17]
	v_pk_fma_f32 v[4:5], v[4:5], v[28:29], v[18:19]
	v_pk_fma_f32 v[6:7], v[6:7], v[30:31], v[14:15]
	s_nop 0
	v_cvt_pk_f16_f32 v7, v6, v7
	v_cvt_pk_f16_f32 v6, v4, v5
	v_cvt_pk_f16_f32 v5, v10, v11
	v_cvt_pk_f16_f32 v4, v8, v9
	global_store_dwordx4 v[20:21], v[4:7], off offset:256
	s_cbranch_vccz .LBB0_653
	s_waitcnt vmcnt(0)
	v_readlane_b32 s48, v251, 13
	s_cmpk_gt_u32 s25, 0xff
	v_readlane_b32 s49, v251, 14
	s_cbranch_scc1 .LBB0_664
	s_barrier
